# GEMM K-loops: the two k-steps of each accumulator issued back to back inside every 32-MFMA segment (accumulate-chain order; same operands and per-accumulator order)
# speedup vs baseline: 1.0125x; 1.0125x over previous
.LBB0_159:
	s_ashr_i32 s29, s28, 31
	s_lshl_b64 s[24:25], s[28:29], 19
	s_add_u32 s24, s34, s24
	s_addc_u32 s25, s35, s25
	s_and_b64 s[30:31], s[18:19], exec
	s_cselect_b32 s29, s25, s41
	s_cselect_b32 s43, s24, s40
	s_ashr_i32 s21, s20, 31
	s_lshl_b64 s[30:31], s[20:21], 19
	s_add_u32 s30, s36, s30
	s_addc_u32 s31, s37, s31
	s_and_b64 s[56:57], s[18:19], exec
	s_cselect_b32 s21, s31, s27
	s_cselect_b32 s55, s30, s26
	s_add_u32 s40, s40, 0x40080
	s_addc_u32 s41, s41, 0
	s_add_u32 s56, s26, 0x100
	s_addc_u32 s57, s27, 0
	s_mov_b32 s58, -2
	s_add_u32 s26, s40, 0xfffc0080
	s_addc_u32 s27, s41, -1
	s_add_i32 s59, 0, 0x10000
	s_cmp_eq_u32 s58, 12
	s_cselect_b32 vcc_hi, s29, s27
	s_cselect_b32 vcc_lo, s43, s26
	v_add_u32_e32 v0, s59, v167
	s_cselect_b32 s27, s21, s57
	s_cselect_b32 s26, s55, s56
	s_add_i32 s62, 0, 0x14000
	ds_read_b128 v[142:145], v0
	ds_read_b128 v[146:149], v0 offset:1024
	ds_read_b128 v[150:153], v0 offset:2048
	ds_read_b128 v[154:157], v0 offset:3072
	v_add_u32_e32 v0, s62, v167
	ds_read_b128 v[158:161], v0
	ds_read_b128 v[162:165], v0 offset:1024
	ds_read_b128 v[174:177], v0 offset:2048
	ds_read_b128 v[178:181], v0 offset:3072
	v_lshl_add_u64 v[214:215], s[40:41], 0, v[138:139]
	s_add_i32 m0, s23, 0xc000
	ds_read_b128 v[182:185], v173
	ds_read_b128 v[186:189], v173 offset:1024
	ds_read_b128 v[190:193], v173 offset:2048
	ds_read_b128 v[194:197], v173 offset:3072
	ds_read_b128 v[198:201], v173 offset:4096
	ds_read_b128 v[202:205], v173 offset:5120
	ds_read_b128 v[206:209], v173 offset:6144
	ds_read_b128 v[210:213], v173 offset:7168
	global_load_lds_dwordx4 v[214:215], off
	v_lshl_add_u64 v[214:215], s[40:41], 0, v[140:141]
	s_add_i32 m0, s23, 0xe000
	s_nop 0
	global_load_lds_dwordx4 v[214:215], off
	s_waitcnt vmcnt(8)
	s_waitcnt lgkmcnt(0)
	s_barrier
	s_waitcnt lgkmcnt(0)
	v_mfma_f32_16x16x32_bf16 v[126:129], v[142:145], v[182:185], 0
	v_mfma_f32_16x16x32_bf16 v[126:129], v[146:149], v[186:189], v[126:129]
	v_mfma_f32_16x16x32_bf16 v[122:125], v[150:153], v[182:185], 0
	v_mfma_f32_16x16x32_bf16 v[122:125], v[154:157], v[186:189], v[122:125]
	v_mfma_f32_16x16x32_bf16 v[118:121], v[142:145], v[190:193], 0
	v_mfma_f32_16x16x32_bf16 v[118:121], v[146:149], v[194:197], v[118:121]
	v_mfma_f32_16x16x32_bf16 v[114:117], v[150:153], v[190:193], 0
	v_mfma_f32_16x16x32_bf16 v[114:117], v[154:157], v[194:197], v[114:117]
	v_mfma_f32_16x16x32_bf16 v[110:113], v[142:145], v[198:201], 0
	v_mfma_f32_16x16x32_bf16 v[110:113], v[146:149], v[202:205], v[110:113]
	v_mfma_f32_16x16x32_bf16 v[106:109], v[150:153], v[198:201], 0
	v_mfma_f32_16x16x32_bf16 v[106:109], v[154:157], v[202:205], v[106:109]
	v_mfma_f32_16x16x32_bf16 v[102:105], v[142:145], v[206:209], 0
	v_mfma_f32_16x16x32_bf16 v[102:105], v[146:149], v[210:213], v[102:105]
	v_mfma_f32_16x16x32_bf16 v[98:101], v[150:153], v[206:209], 0
	v_mfma_f32_16x16x32_bf16 v[98:101], v[154:157], v[210:213], v[98:101]
	v_mfma_f32_16x16x32_bf16 v[82:85], v[158:161], v[182:185], 0
	v_mfma_f32_16x16x32_bf16 v[82:85], v[162:165], v[186:189], v[82:85]
	v_mfma_f32_16x16x32_bf16 v[74:77], v[174:177], v[182:185], 0
	v_mfma_f32_16x16x32_bf16 v[74:77], v[178:181], v[186:189], v[74:77]
	v_mfma_f32_16x16x32_bf16 v[70:73], v[158:161], v[190:193], 0
	v_mfma_f32_16x16x32_bf16 v[70:73], v[162:165], v[194:197], v[70:73]
	v_mfma_f32_16x16x32_bf16 v[62:65], v[174:177], v[190:193], 0
	v_mfma_f32_16x16x32_bf16 v[62:65], v[178:181], v[194:197], v[62:65]
	v_mfma_f32_16x16x32_bf16 v[54:57], v[158:161], v[198:201], 0
	v_mfma_f32_16x16x32_bf16 v[54:57], v[162:165], v[202:205], v[54:57]
	v_mfma_f32_16x16x32_bf16 v[46:49], v[174:177], v[198:201], 0
	v_mfma_f32_16x16x32_bf16 v[46:49], v[178:181], v[202:205], v[46:49]
	v_mfma_f32_16x16x32_bf16 v[38:41], v[158:161], v[206:209], 0
	v_mfma_f32_16x16x32_bf16 v[38:41], v[162:165], v[210:213], v[38:41]
	v_mfma_f32_16x16x32_bf16 v[34:37], v[174:177], v[206:209], 0
	v_mfma_f32_16x16x32_bf16 v[34:37], v[178:181], v[210:213], v[34:37]
	s_barrier
	s_add_i32 s59, s59, s44
	v_lshl_add_u64 v[214:215], s[26:27], 0, v[132:133]
	s_mov_b32 m0, s59
	ds_read_b128 v[182:185], v173 offset:16384
	ds_read_b128 v[186:189], v173 offset:17408
	ds_read_b128 v[190:193], v173 offset:18432
	ds_read_b128 v[194:197], v173 offset:19456
	ds_read_b128 v[198:201], v173 offset:20480
	ds_read_b128 v[202:205], v173 offset:21504
	ds_read_b128 v[206:209], v173 offset:22528
	ds_read_b128 v[210:213], v173 offset:23552
	global_load_lds_dwordx4 v[214:215], off
	s_add_i32 m0, s59, 0x2000
	s_add_u32 s60, s26, 0x40000
	v_lshl_add_u64 v[216:217], s[26:27], 0, v[136:137]
	s_addc_u32 s61, s27, 0
	s_add_i32 s59, s62, s44
	global_load_lds_dwordx4 v[216:217], off
	v_lshl_add_u64 v[218:219], s[60:61], 0, v[132:133]
	s_mov_b32 m0, s59
	v_lshl_add_u64 v[220:221], vcc, 0, v[134:135]
	global_load_lds_dwordx4 v[218:219], off
	v_lshl_add_u64 v[218:219], s[60:61], 0, v[136:137]
	s_add_i32 m0, s59, 0x2000
	s_nop 0
	global_load_lds_dwordx4 v[218:219], off
	v_lshl_add_u64 v[218:219], vcc, 0, v[130:131]
	s_mov_b32 m0, s23
	s_nop 0
	global_load_lds_dwordx4 v[218:219], off
	s_mov_b32 m0, s45
	s_nop 0
	global_load_lds_dwordx4 v[220:221], off
	s_waitcnt vmcnt(8)
	s_waitcnt lgkmcnt(0)
	s_barrier
	s_waitcnt lgkmcnt(0)
	v_mfma_f32_16x16x32_bf16 v[94:97], v[142:145], v[182:185], 0
	v_mfma_f32_16x16x32_bf16 v[94:97], v[146:149], v[186:189], v[94:97]
	v_mfma_f32_16x16x32_bf16 v[90:93], v[150:153], v[182:185], 0
	v_mfma_f32_16x16x32_bf16 v[90:93], v[154:157], v[186:189], v[90:93]
	v_mfma_f32_16x16x32_bf16 v[86:89], v[142:145], v[190:193], 0
	v_mfma_f32_16x16x32_bf16 v[86:89], v[146:149], v[194:197], v[86:89]
	v_mfma_f32_16x16x32_bf16 v[78:81], v[150:153], v[190:193], 0
	v_mfma_f32_16x16x32_bf16 v[78:81], v[154:157], v[194:197], v[78:81]
	v_mfma_f32_16x16x32_bf16 v[66:69], v[142:145], v[198:201], 0
	v_mfma_f32_16x16x32_bf16 v[66:69], v[146:149], v[202:205], v[66:69]
	v_mfma_f32_16x16x32_bf16 v[58:61], v[150:153], v[198:201], 0
	v_mfma_f32_16x16x32_bf16 v[58:61], v[154:157], v[202:205], v[58:61]
	v_mfma_f32_16x16x32_bf16 v[50:53], v[142:145], v[206:209], 0
	v_mfma_f32_16x16x32_bf16 v[50:53], v[146:149], v[210:213], v[50:53]
	v_mfma_f32_16x16x32_bf16 v[42:45], v[150:153], v[206:209], 0
	v_mfma_f32_16x16x32_bf16 v[42:45], v[154:157], v[210:213], v[42:45]
	v_mfma_f32_16x16x32_bf16 v[30:33], v[158:161], v[182:185], 0
	v_mfma_f32_16x16x32_bf16 v[30:33], v[162:165], v[186:189], v[30:33]
	v_mfma_f32_16x16x32_bf16 v[26:29], v[174:177], v[182:185], 0
	v_mfma_f32_16x16x32_bf16 v[26:29], v[178:181], v[186:189], v[26:29]
	v_mfma_f32_16x16x32_bf16 v[22:25], v[158:161], v[190:193], 0
	v_mfma_f32_16x16x32_bf16 v[22:25], v[162:165], v[194:197], v[22:25]
	v_mfma_f32_16x16x32_bf16 v[18:21], v[174:177], v[190:193], 0
	v_mfma_f32_16x16x32_bf16 v[18:21], v[178:181], v[194:197], v[18:21]
	v_mfma_f32_16x16x32_bf16 v[14:17], v[158:161], v[198:201], 0
	v_mfma_f32_16x16x32_bf16 v[14:17], v[162:165], v[202:205], v[14:17]
	v_mfma_f32_16x16x32_bf16 v[10:13], v[174:177], v[198:201], 0
	v_mfma_f32_16x16x32_bf16 v[10:13], v[178:181], v[202:205], v[10:13]
	v_mfma_f32_16x16x32_bf16 v[6:9], v[158:161], v[206:209], 0
	v_mfma_f32_16x16x32_bf16 v[6:9], v[162:165], v[210:213], v[6:9]
	v_mfma_f32_16x16x32_bf16 v[2:5], v[174:177], v[206:209], 0
	v_mfma_f32_16x16x32_bf16 v[2:5], v[178:181], v[210:213], v[2:5]
	s_barrier
	s_add_i32 s59, 0, 0x18000
	v_add_u32_e32 v0, s59, v167
	s_add_i32 s62, 0, 0x1c000
	ds_read_b128 v[142:145], v0
	ds_read_b128 v[146:149], v0 offset:1024
	ds_read_b128 v[150:153], v0 offset:2048
	ds_read_b128 v[154:157], v0 offset:3072
	v_add_u32_e32 v0, s62, v167
	ds_read_b128 v[158:161], v0
	ds_read_b128 v[162:165], v0 offset:1024
	ds_read_b128 v[174:177], v0 offset:2048
	ds_read_b128 v[178:181], v0 offset:3072
	s_add_u32 s60, vcc_lo, 0x40000
	s_addc_u32 s61, vcc_hi, 0
	s_mov_b32 m0, s47
	v_lshl_add_u64 v[222:223], s[60:61], 0, v[130:131]
	ds_read_b128 v[182:185], v173 offset:32768
	ds_read_b128 v[186:189], v173 offset:33792
	ds_read_b128 v[190:193], v173 offset:34816
	ds_read_b128 v[194:197], v173 offset:35840
	ds_read_b128 v[198:201], v173 offset:36864
	ds_read_b128 v[202:205], v173 offset:37888
	ds_read_b128 v[206:209], v173 offset:38912
	ds_read_b128 v[210:213], v173 offset:39936
	global_load_lds_dwordx4 v[222:223], off
	v_lshl_add_u64 v[222:223], s[60:61], 0, v[134:135]
	s_mov_b32 m0, s49
	s_nop 0
	global_load_lds_dwordx4 v[222:223], off
	s_waitcnt vmcnt(8)
	s_waitcnt lgkmcnt(0)
	s_barrier
	s_waitcnt lgkmcnt(0)
	v_mfma_f32_16x16x32_bf16 v[126:129], v[142:145], v[182:185], v[126:129]
	v_mfma_f32_16x16x32_bf16 v[126:129], v[146:149], v[186:189], v[126:129]
	v_mfma_f32_16x16x32_bf16 v[122:125], v[150:153], v[182:185], v[122:125]
	v_mfma_f32_16x16x32_bf16 v[122:125], v[154:157], v[186:189], v[122:125]
	v_mfma_f32_16x16x32_bf16 v[118:121], v[142:145], v[190:193], v[118:121]
	v_mfma_f32_16x16x32_bf16 v[118:121], v[146:149], v[194:197], v[118:121]
	v_mfma_f32_16x16x32_bf16 v[114:117], v[150:153], v[190:193], v[114:117]
	v_mfma_f32_16x16x32_bf16 v[114:117], v[154:157], v[194:197], v[114:117]
	v_mfma_f32_16x16x32_bf16 v[110:113], v[142:145], v[198:201], v[110:113]
	v_mfma_f32_16x16x32_bf16 v[110:113], v[146:149], v[202:205], v[110:113]
	v_mfma_f32_16x16x32_bf16 v[106:109], v[150:153], v[198:201], v[106:109]
	v_mfma_f32_16x16x32_bf16 v[106:109], v[154:157], v[202:205], v[106:109]
	v_mfma_f32_16x16x32_bf16 v[102:105], v[142:145], v[206:209], v[102:105]
	v_mfma_f32_16x16x32_bf16 v[102:105], v[146:149], v[210:213], v[102:105]
	v_mfma_f32_16x16x32_bf16 v[98:101], v[150:153], v[206:209], v[98:101]
	v_mfma_f32_16x16x32_bf16 v[98:101], v[154:157], v[210:213], v[98:101]
	v_mfma_f32_16x16x32_bf16 v[82:85], v[158:161], v[182:185], v[82:85]
	v_mfma_f32_16x16x32_bf16 v[82:85], v[162:165], v[186:189], v[82:85]
	v_mfma_f32_16x16x32_bf16 v[74:77], v[174:177], v[182:185], v[74:77]
	v_mfma_f32_16x16x32_bf16 v[74:77], v[178:181], v[186:189], v[74:77]
	v_mfma_f32_16x16x32_bf16 v[70:73], v[158:161], v[190:193], v[70:73]
	v_mfma_f32_16x16x32_bf16 v[70:73], v[162:165], v[194:197], v[70:73]
	v_mfma_f32_16x16x32_bf16 v[62:65], v[174:177], v[190:193], v[62:65]
	v_mfma_f32_16x16x32_bf16 v[62:65], v[178:181], v[194:197], v[62:65]
	v_mfma_f32_16x16x32_bf16 v[54:57], v[158:161], v[198:201], v[54:57]
	v_mfma_f32_16x16x32_bf16 v[54:57], v[162:165], v[202:205], v[54:57]
	v_mfma_f32_16x16x32_bf16 v[46:49], v[174:177], v[198:201], v[46:49]
	v_mfma_f32_16x16x32_bf16 v[46:49], v[178:181], v[202:205], v[46:49]
	v_mfma_f32_16x16x32_bf16 v[38:41], v[158:161], v[206:209], v[38:41]
	v_mfma_f32_16x16x32_bf16 v[38:41], v[162:165], v[210:213], v[38:41]
	v_mfma_f32_16x16x32_bf16 v[34:37], v[174:177], v[206:209], v[34:37]
	v_mfma_f32_16x16x32_bf16 v[34:37], v[178:181], v[210:213], v[34:37]
	s_barrier
	s_add_i32 s59, s59, s44
	v_lshl_add_u64 v[214:215], v[214:215], 0, s[98:99]
	s_mov_b32 m0, s59
	ds_read_b128 v[182:185], v173 offset:49152
	ds_read_b128 v[186:189], v173 offset:50176
	ds_read_b128 v[190:193], v173 offset:51200
	ds_read_b128 v[194:197], v173 offset:52224
	ds_read_b128 v[198:201], v173 offset:53248
	ds_read_b128 v[202:205], v173 offset:54272
	ds_read_b128 v[206:209], v173 offset:55296
	ds_read_b128 v[210:213], v173 offset:56320
	global_load_lds_dwordx4 v[214:215], off
	s_add_i32 m0, s59, 0x2000
	s_add_u32 s26, s26, 0x40080
	v_lshl_add_u64 v[214:215], v[216:217], 0, s[98:99]
	s_addc_u32 s27, s27, 0
	s_add_i32 s59, s62, s44
	global_load_lds_dwordx4 v[214:215], off
	v_lshl_add_u64 v[214:215], s[26:27], 0, v[132:133]
	s_mov_b32 m0, s59
	s_nop 0
	global_load_lds_dwordx4 v[214:215], off
	v_lshl_add_u64 v[214:215], s[26:27], 0, v[136:137]
	s_add_i32 m0, s59, 0x2000
	s_nop 0
	global_load_lds_dwordx4 v[214:215], off
	v_lshl_add_u64 v[214:215], v[218:219], 0, s[98:99]
	s_mov_b32 m0, s52
	s_nop 0
	global_load_lds_dwordx4 v[214:215], off
	v_lshl_add_u64 v[214:215], v[220:221], 0, s[98:99]
	s_mov_b32 m0, s53
	s_nop 0
	global_load_lds_dwordx4 v[214:215], off
	s_waitcnt vmcnt(8)
	s_waitcnt lgkmcnt(0)
	s_barrier
	s_waitcnt lgkmcnt(0)
	v_mfma_f32_16x16x32_bf16 v[94:97], v[142:145], v[182:185], v[94:97]
	v_mfma_f32_16x16x32_bf16 v[94:97], v[146:149], v[186:189], v[94:97]
	v_mfma_f32_16x16x32_bf16 v[90:93], v[150:153], v[182:185], v[90:93]
	v_mfma_f32_16x16x32_bf16 v[90:93], v[154:157], v[186:189], v[90:93]
	v_mfma_f32_16x16x32_bf16 v[86:89], v[142:145], v[190:193], v[86:89]
	v_mfma_f32_16x16x32_bf16 v[86:89], v[146:149], v[194:197], v[86:89]
	v_mfma_f32_16x16x32_bf16 v[78:81], v[150:153], v[190:193], v[78:81]
	v_mfma_f32_16x16x32_bf16 v[78:81], v[154:157], v[194:197], v[78:81]
	v_mfma_f32_16x16x32_bf16 v[66:69], v[142:145], v[198:201], v[66:69]
	v_mfma_f32_16x16x32_bf16 v[66:69], v[146:149], v[202:205], v[66:69]
	v_mfma_f32_16x16x32_bf16 v[58:61], v[150:153], v[198:201], v[58:61]
	v_mfma_f32_16x16x32_bf16 v[58:61], v[154:157], v[202:205], v[58:61]
	v_mfma_f32_16x16x32_bf16 v[50:53], v[142:145], v[206:209], v[50:53]
	v_mfma_f32_16x16x32_bf16 v[50:53], v[146:149], v[210:213], v[50:53]
	v_mfma_f32_16x16x32_bf16 v[42:45], v[150:153], v[206:209], v[42:45]
	v_mfma_f32_16x16x32_bf16 v[42:45], v[154:157], v[210:213], v[42:45]
	v_mfma_f32_16x16x32_bf16 v[30:33], v[158:161], v[182:185], v[30:33]
	v_mfma_f32_16x16x32_bf16 v[30:33], v[162:165], v[186:189], v[30:33]
	v_mfma_f32_16x16x32_bf16 v[26:29], v[174:177], v[182:185], v[26:29]
	v_mfma_f32_16x16x32_bf16 v[26:29], v[178:181], v[186:189], v[26:29]
	v_mfma_f32_16x16x32_bf16 v[22:25], v[158:161], v[190:193], v[22:25]
	v_mfma_f32_16x16x32_bf16 v[22:25], v[162:165], v[194:197], v[22:25]
	v_mfma_f32_16x16x32_bf16 v[18:21], v[174:177], v[190:193], v[18:21]
	v_mfma_f32_16x16x32_bf16 v[18:21], v[178:181], v[194:197], v[18:21]
	v_mfma_f32_16x16x32_bf16 v[14:17], v[158:161], v[198:201], v[14:17]
	v_mfma_f32_16x16x32_bf16 v[14:17], v[162:165], v[202:205], v[14:17]
	v_mfma_f32_16x16x32_bf16 v[10:13], v[174:177], v[198:201], v[10:13]
	v_mfma_f32_16x16x32_bf16 v[10:13], v[178:181], v[202:205], v[10:13]
	v_mfma_f32_16x16x32_bf16 v[6:9], v[158:161], v[206:209], v[6:9]
	v_mfma_f32_16x16x32_bf16 v[6:9], v[162:165], v[210:213], v[6:9]
	v_mfma_f32_16x16x32_bf16 v[2:5], v[174:177], v[206:209], v[2:5]
	v_mfma_f32_16x16x32_bf16 v[2:5], v[178:181], v[210:213], v[2:5]
	s_barrier
	s_add_i32 s58, s58, 2
	s_add_u32 s40, s40, 0x100
	s_addc_u32 s41, s41, 0
	s_add_u32 s56, s56, 0x100
	s_addc_u32 s57, s57, 0
	s_cmp_gt_u32 s58, 13
	s_cbranch_scc1 .Lpeel_done_160
.LBB0_160:
	s_add_u32 s26, s40, 0xfffc0080
	s_addc_u32 s27, s41, -1
	s_add_i32 s59, 0, 0x10000
	s_cmp_eq_u32 s58, 12
	s_cselect_b32 vcc_hi, s29, s27
	s_cselect_b32 vcc_lo, s43, s26
	v_add_u32_e32 v0, s59, v167
	s_cselect_b32 s27, s21, s57
	s_cselect_b32 s26, s55, s56
	s_add_i32 s62, 0, 0x14000
	ds_read_b128 v[142:145], v0
	ds_read_b128 v[146:149], v0 offset:1024
	ds_read_b128 v[150:153], v0 offset:2048
	ds_read_b128 v[154:157], v0 offset:3072
	v_add_u32_e32 v0, s62, v167
	ds_read_b128 v[158:161], v0
	ds_read_b128 v[162:165], v0 offset:1024
	ds_read_b128 v[174:177], v0 offset:2048
	ds_read_b128 v[178:181], v0 offset:3072
	v_lshl_add_u64 v[214:215], s[40:41], 0, v[138:139]
	s_add_i32 m0, s23, 0xc000
	ds_read_b128 v[182:185], v173
	ds_read_b128 v[186:189], v173 offset:1024
	ds_read_b128 v[190:193], v173 offset:2048
	ds_read_b128 v[194:197], v173 offset:3072
	ds_read_b128 v[198:201], v173 offset:4096
	ds_read_b128 v[202:205], v173 offset:5120
	ds_read_b128 v[206:209], v173 offset:6144
	ds_read_b128 v[210:213], v173 offset:7168
	global_load_lds_dwordx4 v[214:215], off
	v_lshl_add_u64 v[214:215], s[40:41], 0, v[140:141]
	s_add_i32 m0, s23, 0xe000
	s_nop 0
	global_load_lds_dwordx4 v[214:215], off
	s_waitcnt vmcnt(8)
	s_waitcnt lgkmcnt(0)
	s_barrier
	s_waitcnt lgkmcnt(0)
	v_mfma_f32_16x16x32_bf16 v[126:129], v[142:145], v[182:185], v[126:129]
	v_mfma_f32_16x16x32_bf16 v[126:129], v[146:149], v[186:189], v[126:129]
	v_mfma_f32_16x16x32_bf16 v[122:125], v[150:153], v[182:185], v[122:125]
	v_mfma_f32_16x16x32_bf16 v[122:125], v[154:157], v[186:189], v[122:125]
	v_mfma_f32_16x16x32_bf16 v[118:121], v[142:145], v[190:193], v[118:121]
	v_mfma_f32_16x16x32_bf16 v[118:121], v[146:149], v[194:197], v[118:121]
	v_mfma_f32_16x16x32_bf16 v[114:117], v[150:153], v[190:193], v[114:117]
	v_mfma_f32_16x16x32_bf16 v[114:117], v[154:157], v[194:197], v[114:117]
	v_mfma_f32_16x16x32_bf16 v[110:113], v[142:145], v[198:201], v[110:113]
	v_mfma_f32_16x16x32_bf16 v[110:113], v[146:149], v[202:205], v[110:113]
	v_mfma_f32_16x16x32_bf16 v[106:109], v[150:153], v[198:201], v[106:109]
	v_mfma_f32_16x16x32_bf16 v[106:109], v[154:157], v[202:205], v[106:109]
	v_mfma_f32_16x16x32_bf16 v[102:105], v[142:145], v[206:209], v[102:105]
	v_mfma_f32_16x16x32_bf16 v[102:105], v[146:149], v[210:213], v[102:105]
	v_mfma_f32_16x16x32_bf16 v[98:101], v[150:153], v[206:209], v[98:101]
	v_mfma_f32_16x16x32_bf16 v[98:101], v[154:157], v[210:213], v[98:101]
	v_mfma_f32_16x16x32_bf16 v[82:85], v[158:161], v[182:185], v[82:85]
	v_mfma_f32_16x16x32_bf16 v[82:85], v[162:165], v[186:189], v[82:85]
	v_mfma_f32_16x16x32_bf16 v[74:77], v[174:177], v[182:185], v[74:77]
	v_mfma_f32_16x16x32_bf16 v[74:77], v[178:181], v[186:189], v[74:77]
	v_mfma_f32_16x16x32_bf16 v[70:73], v[158:161], v[190:193], v[70:73]
	v_mfma_f32_16x16x32_bf16 v[70:73], v[162:165], v[194:197], v[70:73]
	v_mfma_f32_16x16x32_bf16 v[62:65], v[174:177], v[190:193], v[62:65]
	v_mfma_f32_16x16x32_bf16 v[62:65], v[178:181], v[194:197], v[62:65]
	v_mfma_f32_16x16x32_bf16 v[54:57], v[158:161], v[198:201], v[54:57]
	v_mfma_f32_16x16x32_bf16 v[54:57], v[162:165], v[202:205], v[54:57]
	v_mfma_f32_16x16x32_bf16 v[46:49], v[174:177], v[198:201], v[46:49]
	v_mfma_f32_16x16x32_bf16 v[46:49], v[178:181], v[202:205], v[46:49]
	v_mfma_f32_16x16x32_bf16 v[38:41], v[158:161], v[206:209], v[38:41]
	v_mfma_f32_16x16x32_bf16 v[38:41], v[162:165], v[210:213], v[38:41]
	v_mfma_f32_16x16x32_bf16 v[34:37], v[174:177], v[206:209], v[34:37]
	v_mfma_f32_16x16x32_bf16 v[34:37], v[178:181], v[210:213], v[34:37]
	s_barrier
	s_add_i32 s59, s59, s44
	v_lshl_add_u64 v[214:215], s[26:27], 0, v[132:133]
	s_mov_b32 m0, s59
	ds_read_b128 v[182:185], v173 offset:16384
	ds_read_b128 v[186:189], v173 offset:17408
	ds_read_b128 v[190:193], v173 offset:18432
	ds_read_b128 v[194:197], v173 offset:19456
	ds_read_b128 v[198:201], v173 offset:20480
	ds_read_b128 v[202:205], v173 offset:21504
	ds_read_b128 v[206:209], v173 offset:22528
	ds_read_b128 v[210:213], v173 offset:23552
	global_load_lds_dwordx4 v[214:215], off
	s_add_i32 m0, s59, 0x2000
	s_add_u32 s60, s26, 0x40000
	v_lshl_add_u64 v[216:217], s[26:27], 0, v[136:137]
	s_addc_u32 s61, s27, 0
	s_add_i32 s59, s62, s44
	global_load_lds_dwordx4 v[216:217], off
	v_lshl_add_u64 v[218:219], s[60:61], 0, v[132:133]
	s_mov_b32 m0, s59
	v_lshl_add_u64 v[220:221], vcc, 0, v[134:135]
	global_load_lds_dwordx4 v[218:219], off
	v_lshl_add_u64 v[218:219], s[60:61], 0, v[136:137]
	s_add_i32 m0, s59, 0x2000
	s_nop 0
	global_load_lds_dwordx4 v[218:219], off
	v_lshl_add_u64 v[218:219], vcc, 0, v[130:131]
	s_mov_b32 m0, s23
	s_nop 0
	global_load_lds_dwordx4 v[218:219], off
	s_mov_b32 m0, s45
	s_nop 0
	global_load_lds_dwordx4 v[220:221], off
	s_waitcnt vmcnt(8)
	s_waitcnt lgkmcnt(0)
	s_barrier
	s_waitcnt lgkmcnt(0)
	v_mfma_f32_16x16x32_bf16 v[94:97], v[142:145], v[182:185], v[94:97]
	v_mfma_f32_16x16x32_bf16 v[94:97], v[146:149], v[186:189], v[94:97]
	v_mfma_f32_16x16x32_bf16 v[90:93], v[150:153], v[182:185], v[90:93]
	v_mfma_f32_16x16x32_bf16 v[90:93], v[154:157], v[186:189], v[90:93]
	v_mfma_f32_16x16x32_bf16 v[86:89], v[142:145], v[190:193], v[86:89]
	v_mfma_f32_16x16x32_bf16 v[86:89], v[146:149], v[194:197], v[86:89]
	v_mfma_f32_16x16x32_bf16 v[78:81], v[150:153], v[190:193], v[78:81]
	v_mfma_f32_16x16x32_bf16 v[78:81], v[154:157], v[194:197], v[78:81]
	v_mfma_f32_16x16x32_bf16 v[66:69], v[142:145], v[198:201], v[66:69]
	v_mfma_f32_16x16x32_bf16 v[66:69], v[146:149], v[202:205], v[66:69]
	v_mfma_f32_16x16x32_bf16 v[58:61], v[150:153], v[198:201], v[58:61]
	v_mfma_f32_16x16x32_bf16 v[58:61], v[154:157], v[202:205], v[58:61]
	v_mfma_f32_16x16x32_bf16 v[50:53], v[142:145], v[206:209], v[50:53]
	v_mfma_f32_16x16x32_bf16 v[50:53], v[146:149], v[210:213], v[50:53]
	v_mfma_f32_16x16x32_bf16 v[42:45], v[150:153], v[206:209], v[42:45]
	v_mfma_f32_16x16x32_bf16 v[42:45], v[154:157], v[210:213], v[42:45]
	v_mfma_f32_16x16x32_bf16 v[30:33], v[158:161], v[182:185], v[30:33]
	v_mfma_f32_16x16x32_bf16 v[30:33], v[162:165], v[186:189], v[30:33]
	v_mfma_f32_16x16x32_bf16 v[26:29], v[174:177], v[182:185], v[26:29]
	v_mfma_f32_16x16x32_bf16 v[26:29], v[178:181], v[186:189], v[26:29]
	v_mfma_f32_16x16x32_bf16 v[22:25], v[158:161], v[190:193], v[22:25]
	v_mfma_f32_16x16x32_bf16 v[22:25], v[162:165], v[194:197], v[22:25]
	v_mfma_f32_16x16x32_bf16 v[18:21], v[174:177], v[190:193], v[18:21]
	v_mfma_f32_16x16x32_bf16 v[18:21], v[178:181], v[194:197], v[18:21]
	v_mfma_f32_16x16x32_bf16 v[14:17], v[158:161], v[198:201], v[14:17]
	v_mfma_f32_16x16x32_bf16 v[14:17], v[162:165], v[202:205], v[14:17]
	v_mfma_f32_16x16x32_bf16 v[10:13], v[174:177], v[198:201], v[10:13]
	v_mfma_f32_16x16x32_bf16 v[10:13], v[178:181], v[202:205], v[10:13]
	v_mfma_f32_16x16x32_bf16 v[6:9], v[158:161], v[206:209], v[6:9]
	v_mfma_f32_16x16x32_bf16 v[6:9], v[162:165], v[210:213], v[6:9]
	v_mfma_f32_16x16x32_bf16 v[2:5], v[174:177], v[206:209], v[2:5]
	v_mfma_f32_16x16x32_bf16 v[2:5], v[178:181], v[210:213], v[2:5]
	s_barrier
	s_add_i32 s59, 0, 0x18000
	v_add_u32_e32 v0, s59, v167
	s_add_i32 s62, 0, 0x1c000
	ds_read_b128 v[142:145], v0
	ds_read_b128 v[146:149], v0 offset:1024
	ds_read_b128 v[150:153], v0 offset:2048
	ds_read_b128 v[154:157], v0 offset:3072
	v_add_u32_e32 v0, s62, v167
	ds_read_b128 v[158:161], v0
	ds_read_b128 v[162:165], v0 offset:1024
	ds_read_b128 v[174:177], v0 offset:2048
	ds_read_b128 v[178:181], v0 offset:3072
	s_add_u32 s60, vcc_lo, 0x40000
	s_addc_u32 s61, vcc_hi, 0
	s_mov_b32 m0, s47
	v_lshl_add_u64 v[222:223], s[60:61], 0, v[130:131]
	ds_read_b128 v[182:185], v173 offset:32768
	ds_read_b128 v[186:189], v173 offset:33792
	ds_read_b128 v[190:193], v173 offset:34816
	ds_read_b128 v[194:197], v173 offset:35840
	ds_read_b128 v[198:201], v173 offset:36864
	ds_read_b128 v[202:205], v173 offset:37888
	ds_read_b128 v[206:209], v173 offset:38912
	ds_read_b128 v[210:213], v173 offset:39936
	global_load_lds_dwordx4 v[222:223], off
	v_lshl_add_u64 v[222:223], s[60:61], 0, v[134:135]
	s_mov_b32 m0, s49
	s_nop 0
	global_load_lds_dwordx4 v[222:223], off
	s_waitcnt vmcnt(8)
	s_waitcnt lgkmcnt(0)
	s_barrier
	s_waitcnt lgkmcnt(0)
	v_mfma_f32_16x16x32_bf16 v[126:129], v[142:145], v[182:185], v[126:129]
	v_mfma_f32_16x16x32_bf16 v[126:129], v[146:149], v[186:189], v[126:129]
	v_mfma_f32_16x16x32_bf16 v[122:125], v[150:153], v[182:185], v[122:125]
	v_mfma_f32_16x16x32_bf16 v[122:125], v[154:157], v[186:189], v[122:125]
	v_mfma_f32_16x16x32_bf16 v[118:121], v[142:145], v[190:193], v[118:121]
	v_mfma_f32_16x16x32_bf16 v[118:121], v[146:149], v[194:197], v[118:121]
	v_mfma_f32_16x16x32_bf16 v[114:117], v[150:153], v[190:193], v[114:117]
	v_mfma_f32_16x16x32_bf16 v[114:117], v[154:157], v[194:197], v[114:117]
	v_mfma_f32_16x16x32_bf16 v[110:113], v[142:145], v[198:201], v[110:113]
	v_mfma_f32_16x16x32_bf16 v[110:113], v[146:149], v[202:205], v[110:113]
	v_mfma_f32_16x16x32_bf16 v[106:109], v[150:153], v[198:201], v[106:109]
	v_mfma_f32_16x16x32_bf16 v[106:109], v[154:157], v[202:205], v[106:109]
	v_mfma_f32_16x16x32_bf16 v[102:105], v[142:145], v[206:209], v[102:105]
	v_mfma_f32_16x16x32_bf16 v[102:105], v[146:149], v[210:213], v[102:105]
	v_mfma_f32_16x16x32_bf16 v[98:101], v[150:153], v[206:209], v[98:101]
	v_mfma_f32_16x16x32_bf16 v[98:101], v[154:157], v[210:213], v[98:101]
	v_mfma_f32_16x16x32_bf16 v[82:85], v[158:161], v[182:185], v[82:85]
	v_mfma_f32_16x16x32_bf16 v[82:85], v[162:165], v[186:189], v[82:85]
	v_mfma_f32_16x16x32_bf16 v[74:77], v[174:177], v[182:185], v[74:77]
	v_mfma_f32_16x16x32_bf16 v[74:77], v[178:181], v[186:189], v[74:77]
	v_mfma_f32_16x16x32_bf16 v[70:73], v[158:161], v[190:193], v[70:73]
	v_mfma_f32_16x16x32_bf16 v[70:73], v[162:165], v[194:197], v[70:73]
	v_mfma_f32_16x16x32_bf16 v[62:65], v[174:177], v[190:193], v[62:65]
	v_mfma_f32_16x16x32_bf16 v[62:65], v[178:181], v[194:197], v[62:65]
	v_mfma_f32_16x16x32_bf16 v[54:57], v[158:161], v[198:201], v[54:57]
	v_mfma_f32_16x16x32_bf16 v[54:57], v[162:165], v[202:205], v[54:57]
	v_mfma_f32_16x16x32_bf16 v[46:49], v[174:177], v[198:201], v[46:49]
	v_mfma_f32_16x16x32_bf16 v[46:49], v[178:181], v[202:205], v[46:49]
	v_mfma_f32_16x16x32_bf16 v[38:41], v[158:161], v[206:209], v[38:41]
	v_mfma_f32_16x16x32_bf16 v[38:41], v[162:165], v[210:213], v[38:41]
	v_mfma_f32_16x16x32_bf16 v[34:37], v[174:177], v[206:209], v[34:37]
	v_mfma_f32_16x16x32_bf16 v[34:37], v[178:181], v[210:213], v[34:37]
	s_barrier
	s_add_i32 s59, s59, s44
	v_lshl_add_u64 v[214:215], v[214:215], 0, s[98:99]
	s_mov_b32 m0, s59
	ds_read_b128 v[182:185], v173 offset:49152
	ds_read_b128 v[186:189], v173 offset:50176
	ds_read_b128 v[190:193], v173 offset:51200
	ds_read_b128 v[194:197], v173 offset:52224
	ds_read_b128 v[198:201], v173 offset:53248
	ds_read_b128 v[202:205], v173 offset:54272
	ds_read_b128 v[206:209], v173 offset:55296
	ds_read_b128 v[210:213], v173 offset:56320
	global_load_lds_dwordx4 v[214:215], off
	s_add_i32 m0, s59, 0x2000
	s_add_u32 s26, s26, 0x40080
	v_lshl_add_u64 v[214:215], v[216:217], 0, s[98:99]
	s_addc_u32 s27, s27, 0
	s_add_i32 s59, s62, s44
	global_load_lds_dwordx4 v[214:215], off
	v_lshl_add_u64 v[214:215], s[26:27], 0, v[132:133]
	s_mov_b32 m0, s59
	s_nop 0
	global_load_lds_dwordx4 v[214:215], off
	v_lshl_add_u64 v[214:215], s[26:27], 0, v[136:137]
	s_add_i32 m0, s59, 0x2000
	s_nop 0
	global_load_lds_dwordx4 v[214:215], off
	v_lshl_add_u64 v[214:215], v[218:219], 0, s[98:99]
	s_mov_b32 m0, s52
	s_nop 0
	global_load_lds_dwordx4 v[214:215], off
	v_lshl_add_u64 v[214:215], v[220:221], 0, s[98:99]
	s_mov_b32 m0, s53
	s_nop 0
	global_load_lds_dwordx4 v[214:215], off
	s_waitcnt vmcnt(8)
	s_waitcnt lgkmcnt(0)
	s_barrier
	s_waitcnt lgkmcnt(0)
	v_mfma_f32_16x16x32_bf16 v[94:97], v[142:145], v[182:185], v[94:97]
	v_mfma_f32_16x16x32_bf16 v[94:97], v[146:149], v[186:189], v[94:97]
	v_mfma_f32_16x16x32_bf16 v[90:93], v[150:153], v[182:185], v[90:93]
	v_mfma_f32_16x16x32_bf16 v[90:93], v[154:157], v[186:189], v[90:93]
	v_mfma_f32_16x16x32_bf16 v[86:89], v[142:145], v[190:193], v[86:89]
	v_mfma_f32_16x16x32_bf16 v[86:89], v[146:149], v[194:197], v[86:89]
	v_mfma_f32_16x16x32_bf16 v[78:81], v[150:153], v[190:193], v[78:81]
	v_mfma_f32_16x16x32_bf16 v[78:81], v[154:157], v[194:197], v[78:81]
	v_mfma_f32_16x16x32_bf16 v[66:69], v[142:145], v[198:201], v[66:69]
	v_mfma_f32_16x16x32_bf16 v[66:69], v[146:149], v[202:205], v[66:69]
	v_mfma_f32_16x16x32_bf16 v[58:61], v[150:153], v[198:201], v[58:61]
	v_mfma_f32_16x16x32_bf16 v[58:61], v[154:157], v[202:205], v[58:61]
	v_mfma_f32_16x16x32_bf16 v[50:53], v[142:145], v[206:209], v[50:53]
	v_mfma_f32_16x16x32_bf16 v[50:53], v[146:149], v[210:213], v[50:53]
	v_mfma_f32_16x16x32_bf16 v[42:45], v[150:153], v[206:209], v[42:45]
	v_mfma_f32_16x16x32_bf16 v[42:45], v[154:157], v[210:213], v[42:45]
	v_mfma_f32_16x16x32_bf16 v[30:33], v[158:161], v[182:185], v[30:33]
	v_mfma_f32_16x16x32_bf16 v[30:33], v[162:165], v[186:189], v[30:33]
	v_mfma_f32_16x16x32_bf16 v[26:29], v[174:177], v[182:185], v[26:29]
	v_mfma_f32_16x16x32_bf16 v[26:29], v[178:181], v[186:189], v[26:29]
	v_mfma_f32_16x16x32_bf16 v[22:25], v[158:161], v[190:193], v[22:25]
	v_mfma_f32_16x16x32_bf16 v[22:25], v[162:165], v[194:197], v[22:25]
	v_mfma_f32_16x16x32_bf16 v[18:21], v[174:177], v[190:193], v[18:21]
	v_mfma_f32_16x16x32_bf16 v[18:21], v[178:181], v[194:197], v[18:21]
	v_mfma_f32_16x16x32_bf16 v[14:17], v[158:161], v[198:201], v[14:17]
	v_mfma_f32_16x16x32_bf16 v[14:17], v[162:165], v[202:205], v[14:17]
	v_mfma_f32_16x16x32_bf16 v[10:13], v[174:177], v[198:201], v[10:13]
	v_mfma_f32_16x16x32_bf16 v[10:13], v[178:181], v[202:205], v[10:13]
	v_mfma_f32_16x16x32_bf16 v[6:9], v[158:161], v[206:209], v[6:9]
	v_mfma_f32_16x16x32_bf16 v[6:9], v[162:165], v[210:213], v[6:9]
	v_mfma_f32_16x16x32_bf16 v[2:5], v[174:177], v[206:209], v[2:5]
	v_mfma_f32_16x16x32_bf16 v[2:5], v[178:181], v[210:213], v[2:5]
	s_barrier
	s_add_i32 s58, s58, 2
	s_add_u32 s40, s40, 0x100
	s_addc_u32 s41, s41, 0
	s_add_u32 s56, s56, 0x100
	s_addc_u32 s57, s57, 0
	s_cmp_gt_u32 s58, 13
	s_cbranch_scc0 .LBB0_160

.LBB0_216:
	s_add_i32 s13, s61, -2
	s_add_u32 s28, s28, 0x80
	s_addc_u32 s29, s29, 0
	s_add_u32 s23, s40, 0x100
	s_addc_u32 s40, s41, 0
	s_mov_b32 s30, 0
	s_add_i32 s41, s30, 2
	s_add_u32 vcc_lo, s28, 0x80
	s_addc_u32 s31, s29, 0
	s_add_i32 s62, 0, 0x10000
	s_cmp_eq_u32 s13, s30
	s_cselect_b32 s31, s25, s31
	s_cselect_b32 s30, s24, vcc_lo
	v_add_u32_e32 v145, s62, v175
	s_cselect_b32 vcc_hi, s27, s40
	s_cselect_b32 vcc_lo, s26, s23
	s_add_i32 s63, 0, 0x14000
	ds_read_b128 v[130:133], v145
	ds_read_b128 v[134:137], v145 offset:1024
	ds_read_b128 v[152:155], v145 offset:2048
	ds_read_b128 v[156:159], v145 offset:3072
	v_add_u32_e32 v145, s63, v175
	ds_read_b128 v[160:163], v145
	ds_read_b128 v[164:167], v145 offset:1024
	ds_read_b128 v[168:171], v145 offset:2048
	ds_read_b128 v[186:189], v145 offset:3072
	v_lshl_add_u64 v[172:173], s[28:29], 0, v[148:149]
	s_add_i32 m0, s93, 0xc000
	ds_read_b128 v[190:193], v184
	ds_read_b128 v[194:197], v184 offset:1024
	ds_read_b128 v[198:201], v184 offset:2048
	ds_read_b128 v[202:205], v184 offset:3072
	ds_read_b128 v[206:209], v184 offset:4096
	ds_read_b128 v[210:213], v184 offset:5120
	ds_read_b128 v[214:217], v184 offset:6144
	ds_read_b128 v[218:221], v184 offset:7168
	global_load_lds_dwordx4 v[172:173], off
	v_lshl_add_u64 v[172:173], s[28:29], 0, v[150:151]
	s_add_i32 m0, s93, 0xe000
	s_nop 0
	global_load_lds_dwordx4 v[172:173], off
	s_waitcnt vmcnt(8)
	s_waitcnt lgkmcnt(0)
	s_barrier
	s_waitcnt lgkmcnt(0)
	v_mfma_f32_16x16x32_bf16 v[126:129], v[130:133], v[190:193], 0
	v_mfma_f32_16x16x32_bf16 v[126:129], v[134:137], v[194:197], v[126:129]
	v_mfma_f32_16x16x32_bf16 v[122:125], v[152:155], v[190:193], 0
	v_mfma_f32_16x16x32_bf16 v[122:125], v[156:159], v[194:197], v[122:125]
	v_mfma_f32_16x16x32_bf16 v[110:113], v[130:133], v[198:201], 0
	v_mfma_f32_16x16x32_bf16 v[110:113], v[134:137], v[202:205], v[110:113]
	v_mfma_f32_16x16x32_bf16 v[106:109], v[152:155], v[198:201], 0
	v_mfma_f32_16x16x32_bf16 v[106:109], v[156:159], v[202:205], v[106:109]
	v_mfma_f32_16x16x32_bf16 v[94:97], v[130:133], v[206:209], 0
	v_mfma_f32_16x16x32_bf16 v[94:97], v[134:137], v[210:213], v[94:97]
	v_mfma_f32_16x16x32_bf16 v[90:93], v[152:155], v[206:209], 0
	v_mfma_f32_16x16x32_bf16 v[90:93], v[156:159], v[210:213], v[90:93]
	v_mfma_f32_16x16x32_bf16 v[78:81], v[130:133], v[214:217], 0
	v_mfma_f32_16x16x32_bf16 v[78:81], v[134:137], v[218:221], v[78:81]
	v_mfma_f32_16x16x32_bf16 v[74:77], v[152:155], v[214:217], 0
	v_mfma_f32_16x16x32_bf16 v[74:77], v[156:159], v[218:221], v[74:77]
	v_mfma_f32_16x16x32_bf16 v[118:121], v[160:163], v[190:193], 0
	v_mfma_f32_16x16x32_bf16 v[118:121], v[164:167], v[194:197], v[118:121]
	v_mfma_f32_16x16x32_bf16 v[114:117], v[168:171], v[190:193], 0
	v_mfma_f32_16x16x32_bf16 v[114:117], v[186:189], v[194:197], v[114:117]
	v_mfma_f32_16x16x32_bf16 v[102:105], v[160:163], v[198:201], 0
	v_mfma_f32_16x16x32_bf16 v[102:105], v[164:167], v[202:205], v[102:105]
	v_mfma_f32_16x16x32_bf16 v[98:101], v[168:171], v[198:201], 0
	v_mfma_f32_16x16x32_bf16 v[98:101], v[186:189], v[202:205], v[98:101]
	v_mfma_f32_16x16x32_bf16 v[86:89], v[160:163], v[206:209], 0
	v_mfma_f32_16x16x32_bf16 v[86:89], v[164:167], v[210:213], v[86:89]
	v_mfma_f32_16x16x32_bf16 v[82:85], v[168:171], v[206:209], 0
	v_mfma_f32_16x16x32_bf16 v[82:85], v[186:189], v[210:213], v[82:85]
	v_mfma_f32_16x16x32_bf16 v[70:73], v[160:163], v[214:217], 0
	v_mfma_f32_16x16x32_bf16 v[70:73], v[164:167], v[218:221], v[70:73]
	v_mfma_f32_16x16x32_bf16 v[66:69], v[168:171], v[214:217], 0
	v_mfma_f32_16x16x32_bf16 v[66:69], v[186:189], v[218:221], v[66:69]
	s_barrier
	s_add_i32 s62, s62, s49
	v_lshl_add_u64 v[172:173], vcc, 0, v[0:1]
	s_mov_b32 m0, s62
	ds_read_b128 v[190:193], v184 offset:16384
	ds_read_b128 v[194:197], v184 offset:17408
	ds_read_b128 v[198:201], v184 offset:18432
	ds_read_b128 v[202:205], v184 offset:19456
	ds_read_b128 v[206:209], v184 offset:20480
	ds_read_b128 v[210:213], v184 offset:21504
	ds_read_b128 v[214:217], v184 offset:22528
	ds_read_b128 v[218:221], v184 offset:23552
	global_load_lds_dwordx4 v[172:173], off
	s_add_i32 m0, s62, 0x2000
	v_lshl_add_u64 v[222:223], vcc, 0, v[142:143]
	s_add_u32 vcc_lo, vcc_lo, s96
	s_addc_u32 vcc_hi, vcc_hi, 0
	s_add_i32 s62, s63, s49
	global_load_lds_dwordx4 v[222:223], off
	v_lshl_add_u64 v[236:237], vcc, 0, v[0:1]
	s_mov_b32 m0, s62
	v_lshl_add_u64 v[238:239], vcc, 0, v[142:143]
	global_load_lds_dwordx4 v[236:237], off
	s_add_i32 m0, s62, 0x2000
	v_lshl_add_u64 v[240:241], s[30:31], 0, v[138:139]
	global_load_lds_dwordx4 v[238:239], off
	s_mov_b32 m0, s93
	v_lshl_add_u64 v[242:243], s[30:31], 0, v[140:141]
	global_load_lds_dwordx4 v[240:241], off
	s_mov_b32 m0, s88
	s_nop 0
	global_load_lds_dwordx4 v[242:243], off
	s_waitcnt vmcnt(8)
	s_waitcnt lgkmcnt(0)
	s_barrier
	s_waitcnt lgkmcnt(0)
	v_mfma_f32_16x16x32_bf16 v[62:65], v[130:133], v[190:193], 0
	v_mfma_f32_16x16x32_bf16 v[62:65], v[134:137], v[194:197], v[62:65]
	v_mfma_f32_16x16x32_bf16 v[58:61], v[152:155], v[190:193], 0
	v_mfma_f32_16x16x32_bf16 v[58:61], v[156:159], v[194:197], v[58:61]
	v_mfma_f32_16x16x32_bf16 v[46:49], v[130:133], v[198:201], 0
	v_mfma_f32_16x16x32_bf16 v[46:49], v[134:137], v[202:205], v[46:49]
	v_mfma_f32_16x16x32_bf16 v[42:45], v[152:155], v[198:201], 0
	v_mfma_f32_16x16x32_bf16 v[42:45], v[156:159], v[202:205], v[42:45]
	v_mfma_f32_16x16x32_bf16 v[30:33], v[130:133], v[206:209], 0
	v_mfma_f32_16x16x32_bf16 v[30:33], v[134:137], v[210:213], v[30:33]
	v_mfma_f32_16x16x32_bf16 v[26:29], v[152:155], v[206:209], 0
	v_mfma_f32_16x16x32_bf16 v[26:29], v[156:159], v[210:213], v[26:29]
	v_mfma_f32_16x16x32_bf16 v[14:17], v[130:133], v[214:217], 0
	v_mfma_f32_16x16x32_bf16 v[14:17], v[134:137], v[218:221], v[14:17]
	v_mfma_f32_16x16x32_bf16 v[10:13], v[152:155], v[214:217], 0
	v_mfma_f32_16x16x32_bf16 v[10:13], v[156:159], v[218:221], v[10:13]
	v_mfma_f32_16x16x32_bf16 v[54:57], v[160:163], v[190:193], 0
	v_mfma_f32_16x16x32_bf16 v[54:57], v[164:167], v[194:197], v[54:57]
	v_mfma_f32_16x16x32_bf16 v[50:53], v[168:171], v[190:193], 0
	v_mfma_f32_16x16x32_bf16 v[50:53], v[186:189], v[194:197], v[50:53]
	v_mfma_f32_16x16x32_bf16 v[38:41], v[160:163], v[198:201], 0
	v_mfma_f32_16x16x32_bf16 v[38:41], v[164:167], v[202:205], v[38:41]
	v_mfma_f32_16x16x32_bf16 v[34:37], v[168:171], v[198:201], 0
	v_mfma_f32_16x16x32_bf16 v[34:37], v[186:189], v[202:205], v[34:37]
	v_mfma_f32_16x16x32_bf16 v[22:25], v[160:163], v[206:209], 0
	v_mfma_f32_16x16x32_bf16 v[22:25], v[164:167], v[210:213], v[22:25]
	v_mfma_f32_16x16x32_bf16 v[18:21], v[168:171], v[206:209], 0
	v_mfma_f32_16x16x32_bf16 v[18:21], v[186:189], v[210:213], v[18:21]
	v_mfma_f32_16x16x32_bf16 v[6:9], v[160:163], v[214:217], 0
	v_mfma_f32_16x16x32_bf16 v[6:9], v[164:167], v[218:221], v[6:9]
	v_mfma_f32_16x16x32_bf16 v[2:5], v[168:171], v[214:217], 0
	v_mfma_f32_16x16x32_bf16 v[2:5], v[186:189], v[218:221], v[2:5]
	s_barrier
	s_add_i32 s62, 0, 0x18000
	v_add_u32_e32 v145, s62, v175
	s_add_i32 s63, 0, 0x1c000
	ds_read_b128 v[130:133], v145
	ds_read_b128 v[134:137], v145 offset:1024
	ds_read_b128 v[152:155], v145 offset:2048
	ds_read_b128 v[156:159], v145 offset:3072
	v_add_u32_e32 v145, s63, v175
	ds_read_b128 v[160:163], v145
	ds_read_b128 v[164:167], v145 offset:1024
	ds_read_b128 v[168:171], v145 offset:2048
	ds_read_b128 v[186:189], v145 offset:3072
	s_add_u32 s30, s30, s96
	s_addc_u32 s31, s31, 0
	s_mov_b32 m0, s89
	v_lshl_add_u64 v[244:245], s[30:31], 0, v[138:139]
	ds_read_b128 v[190:193], v184 offset:32768
	ds_read_b128 v[194:197], v184 offset:33792
	ds_read_b128 v[198:201], v184 offset:34816
	ds_read_b128 v[202:205], v184 offset:35840
	ds_read_b128 v[206:209], v184 offset:36864
	ds_read_b128 v[210:213], v184 offset:37888
	ds_read_b128 v[214:217], v184 offset:38912
	ds_read_b128 v[218:221], v184 offset:39936
	global_load_lds_dwordx4 v[244:245], off
	v_lshl_add_u64 v[244:245], s[30:31], 0, v[140:141]
	s_mov_b32 m0, s52
	s_nop 0
	global_load_lds_dwordx4 v[244:245], off
	s_waitcnt vmcnt(8)
	s_waitcnt lgkmcnt(0)
	s_barrier
	s_waitcnt lgkmcnt(0)
	v_mfma_f32_16x16x32_bf16 v[126:129], v[130:133], v[190:193], v[126:129]
	v_mfma_f32_16x16x32_bf16 v[126:129], v[134:137], v[194:197], v[126:129]
	v_mfma_f32_16x16x32_bf16 v[122:125], v[152:155], v[190:193], v[122:125]
	v_mfma_f32_16x16x32_bf16 v[122:125], v[156:159], v[194:197], v[122:125]
	v_mfma_f32_16x16x32_bf16 v[110:113], v[130:133], v[198:201], v[110:113]
	v_mfma_f32_16x16x32_bf16 v[110:113], v[134:137], v[202:205], v[110:113]
	v_mfma_f32_16x16x32_bf16 v[106:109], v[152:155], v[198:201], v[106:109]
	v_mfma_f32_16x16x32_bf16 v[106:109], v[156:159], v[202:205], v[106:109]
	v_mfma_f32_16x16x32_bf16 v[94:97], v[130:133], v[206:209], v[94:97]
	v_mfma_f32_16x16x32_bf16 v[94:97], v[134:137], v[210:213], v[94:97]
	v_mfma_f32_16x16x32_bf16 v[90:93], v[152:155], v[206:209], v[90:93]
	v_mfma_f32_16x16x32_bf16 v[90:93], v[156:159], v[210:213], v[90:93]
	v_mfma_f32_16x16x32_bf16 v[78:81], v[130:133], v[214:217], v[78:81]
	v_mfma_f32_16x16x32_bf16 v[78:81], v[134:137], v[218:221], v[78:81]
	v_mfma_f32_16x16x32_bf16 v[74:77], v[152:155], v[214:217], v[74:77]
	v_mfma_f32_16x16x32_bf16 v[74:77], v[156:159], v[218:221], v[74:77]
	v_mfma_f32_16x16x32_bf16 v[118:121], v[160:163], v[190:193], v[118:121]
	v_mfma_f32_16x16x32_bf16 v[118:121], v[164:167], v[194:197], v[118:121]
	v_mfma_f32_16x16x32_bf16 v[114:117], v[168:171], v[190:193], v[114:117]
	v_mfma_f32_16x16x32_bf16 v[114:117], v[186:189], v[194:197], v[114:117]
	v_mfma_f32_16x16x32_bf16 v[102:105], v[160:163], v[198:201], v[102:105]
	v_mfma_f32_16x16x32_bf16 v[102:105], v[164:167], v[202:205], v[102:105]
	v_mfma_f32_16x16x32_bf16 v[98:101], v[168:171], v[198:201], v[98:101]
	v_mfma_f32_16x16x32_bf16 v[98:101], v[186:189], v[202:205], v[98:101]
	v_mfma_f32_16x16x32_bf16 v[86:89], v[160:163], v[206:209], v[86:89]
	v_mfma_f32_16x16x32_bf16 v[86:89], v[164:167], v[210:213], v[86:89]
	v_mfma_f32_16x16x32_bf16 v[82:85], v[168:171], v[206:209], v[82:85]
	v_mfma_f32_16x16x32_bf16 v[82:85], v[186:189], v[210:213], v[82:85]
	v_mfma_f32_16x16x32_bf16 v[70:73], v[160:163], v[214:217], v[70:73]
	v_mfma_f32_16x16x32_bf16 v[70:73], v[164:167], v[218:221], v[70:73]
	v_mfma_f32_16x16x32_bf16 v[66:69], v[168:171], v[214:217], v[66:69]
	v_mfma_f32_16x16x32_bf16 v[66:69], v[186:189], v[218:221], v[66:69]
	s_barrier
	s_add_i32 s30, s62, s49
	v_lshl_add_u64 v[172:173], v[172:173], 0, s[98:99]
	s_mov_b32 m0, s30
	ds_read_b128 v[190:193], v184 offset:49152
	ds_read_b128 v[194:197], v184 offset:50176
	ds_read_b128 v[198:201], v184 offset:51200
	ds_read_b128 v[202:205], v184 offset:52224
	ds_read_b128 v[206:209], v184 offset:53248
	ds_read_b128 v[210:213], v184 offset:54272
	ds_read_b128 v[214:217], v184 offset:55296
	ds_read_b128 v[218:221], v184 offset:56320
	global_load_lds_dwordx4 v[172:173], off
	v_lshl_add_u64 v[172:173], v[222:223], 0, s[98:99]
	s_add_i32 m0, s30, 0x2000
	s_add_i32 s30, s63, s49
	global_load_lds_dwordx4 v[172:173], off
	v_lshl_add_u64 v[172:173], v[236:237], 0, s[98:99]
	s_mov_b32 m0, s30
	s_nop 0
	global_load_lds_dwordx4 v[172:173], off
	v_lshl_add_u64 v[172:173], v[238:239], 0, s[98:99]
	s_add_i32 m0, s30, 0x2000
	s_nop 0
	global_load_lds_dwordx4 v[172:173], off
	v_lshl_add_u64 v[172:173], v[240:241], 0, s[98:99]
	s_mov_b32 m0, s95
	s_nop 0
	global_load_lds_dwordx4 v[172:173], off
	v_lshl_add_u64 v[172:173], v[242:243], 0, s[98:99]
	s_mov_b32 m0, s54
	s_nop 0
	global_load_lds_dwordx4 v[172:173], off
	s_waitcnt vmcnt(8)
	s_waitcnt lgkmcnt(0)
	s_barrier
	s_waitcnt lgkmcnt(0)
	v_mfma_f32_16x16x32_bf16 v[62:65], v[130:133], v[190:193], v[62:65]
	v_mfma_f32_16x16x32_bf16 v[62:65], v[134:137], v[194:197], v[62:65]
	v_mfma_f32_16x16x32_bf16 v[58:61], v[152:155], v[190:193], v[58:61]
	v_mfma_f32_16x16x32_bf16 v[58:61], v[156:159], v[194:197], v[58:61]
	v_mfma_f32_16x16x32_bf16 v[46:49], v[130:133], v[198:201], v[46:49]
	v_mfma_f32_16x16x32_bf16 v[46:49], v[134:137], v[202:205], v[46:49]
	v_mfma_f32_16x16x32_bf16 v[42:45], v[152:155], v[198:201], v[42:45]
	v_mfma_f32_16x16x32_bf16 v[42:45], v[156:159], v[202:205], v[42:45]
	v_mfma_f32_16x16x32_bf16 v[30:33], v[130:133], v[206:209], v[30:33]
	v_mfma_f32_16x16x32_bf16 v[30:33], v[134:137], v[210:213], v[30:33]
	v_mfma_f32_16x16x32_bf16 v[26:29], v[152:155], v[206:209], v[26:29]
	v_mfma_f32_16x16x32_bf16 v[26:29], v[156:159], v[210:213], v[26:29]
	v_mfma_f32_16x16x32_bf16 v[14:17], v[130:133], v[214:217], v[14:17]
	v_mfma_f32_16x16x32_bf16 v[14:17], v[134:137], v[218:221], v[14:17]
	v_mfma_f32_16x16x32_bf16 v[10:13], v[152:155], v[214:217], v[10:13]
	v_mfma_f32_16x16x32_bf16 v[10:13], v[156:159], v[218:221], v[10:13]
	v_mfma_f32_16x16x32_bf16 v[54:57], v[160:163], v[190:193], v[54:57]
	v_mfma_f32_16x16x32_bf16 v[54:57], v[164:167], v[194:197], v[54:57]
	v_mfma_f32_16x16x32_bf16 v[50:53], v[168:171], v[190:193], v[50:53]
	v_mfma_f32_16x16x32_bf16 v[50:53], v[186:189], v[194:197], v[50:53]
	v_mfma_f32_16x16x32_bf16 v[38:41], v[160:163], v[198:201], v[38:41]
	v_mfma_f32_16x16x32_bf16 v[38:41], v[164:167], v[202:205], v[38:41]
	v_mfma_f32_16x16x32_bf16 v[34:37], v[168:171], v[198:201], v[34:37]
	v_mfma_f32_16x16x32_bf16 v[34:37], v[186:189], v[202:205], v[34:37]
	v_mfma_f32_16x16x32_bf16 v[22:25], v[160:163], v[206:209], v[22:25]
	v_mfma_f32_16x16x32_bf16 v[22:25], v[164:167], v[210:213], v[22:25]
	v_mfma_f32_16x16x32_bf16 v[18:21], v[168:171], v[206:209], v[18:21]
	v_mfma_f32_16x16x32_bf16 v[18:21], v[186:189], v[210:213], v[18:21]
	v_mfma_f32_16x16x32_bf16 v[6:9], v[160:163], v[214:217], v[6:9]
	v_mfma_f32_16x16x32_bf16 v[6:9], v[164:167], v[218:221], v[6:9]
	v_mfma_f32_16x16x32_bf16 v[2:5], v[168:171], v[214:217], v[2:5]
	v_mfma_f32_16x16x32_bf16 v[2:5], v[186:189], v[218:221], v[2:5]
	s_barrier
	s_add_u32 s28, s28, 0x100
	s_addc_u32 s29, s29, 0
	s_add_u32 s23, s23, 0x100
	s_addc_u32 s40, s40, 0
	s_cmp_ge_i32 s41, s61
	s_mov_b32 s30, s41
	s_cbranch_scc1 .Lpeel_done_217
.LBB0_217:
	s_add_i32 s41, s30, 2
	s_add_u32 vcc_lo, s28, 0x80
	s_addc_u32 s31, s29, 0
	s_add_i32 s62, 0, 0x10000
	s_cmp_eq_u32 s13, s30
	s_cselect_b32 s31, s25, s31
	s_cselect_b32 s30, s24, vcc_lo
	v_add_u32_e32 v145, s62, v175
	s_cselect_b32 vcc_hi, s27, s40
	s_cselect_b32 vcc_lo, s26, s23
	s_add_i32 s63, 0, 0x14000
	ds_read_b128 v[130:133], v145
	ds_read_b128 v[134:137], v145 offset:1024
	ds_read_b128 v[152:155], v145 offset:2048
	ds_read_b128 v[156:159], v145 offset:3072
	v_add_u32_e32 v145, s63, v175
	ds_read_b128 v[160:163], v145
	ds_read_b128 v[164:167], v145 offset:1024
	ds_read_b128 v[168:171], v145 offset:2048
	ds_read_b128 v[186:189], v145 offset:3072
	v_lshl_add_u64 v[172:173], s[28:29], 0, v[148:149]
	s_add_i32 m0, s93, 0xc000
	ds_read_b128 v[190:193], v184
	ds_read_b128 v[194:197], v184 offset:1024
	ds_read_b128 v[198:201], v184 offset:2048
	ds_read_b128 v[202:205], v184 offset:3072
	ds_read_b128 v[206:209], v184 offset:4096
	ds_read_b128 v[210:213], v184 offset:5120
	ds_read_b128 v[214:217], v184 offset:6144
	ds_read_b128 v[218:221], v184 offset:7168
	global_load_lds_dwordx4 v[172:173], off
	v_lshl_add_u64 v[172:173], s[28:29], 0, v[150:151]
	s_add_i32 m0, s93, 0xe000
	s_nop 0
	global_load_lds_dwordx4 v[172:173], off
	s_waitcnt vmcnt(8)
	s_waitcnt lgkmcnt(0)
	s_barrier
	s_waitcnt lgkmcnt(0)
	v_mfma_f32_16x16x32_bf16 v[126:129], v[130:133], v[190:193], v[126:129]
	v_mfma_f32_16x16x32_bf16 v[126:129], v[134:137], v[194:197], v[126:129]
	v_mfma_f32_16x16x32_bf16 v[122:125], v[152:155], v[190:193], v[122:125]
	v_mfma_f32_16x16x32_bf16 v[122:125], v[156:159], v[194:197], v[122:125]
	v_mfma_f32_16x16x32_bf16 v[110:113], v[130:133], v[198:201], v[110:113]
	v_mfma_f32_16x16x32_bf16 v[110:113], v[134:137], v[202:205], v[110:113]
	v_mfma_f32_16x16x32_bf16 v[106:109], v[152:155], v[198:201], v[106:109]
	v_mfma_f32_16x16x32_bf16 v[106:109], v[156:159], v[202:205], v[106:109]
	v_mfma_f32_16x16x32_bf16 v[94:97], v[130:133], v[206:209], v[94:97]
	v_mfma_f32_16x16x32_bf16 v[94:97], v[134:137], v[210:213], v[94:97]
	v_mfma_f32_16x16x32_bf16 v[90:93], v[152:155], v[206:209], v[90:93]
	v_mfma_f32_16x16x32_bf16 v[90:93], v[156:159], v[210:213], v[90:93]
	v_mfma_f32_16x16x32_bf16 v[78:81], v[130:133], v[214:217], v[78:81]
	v_mfma_f32_16x16x32_bf16 v[78:81], v[134:137], v[218:221], v[78:81]
	v_mfma_f32_16x16x32_bf16 v[74:77], v[152:155], v[214:217], v[74:77]
	v_mfma_f32_16x16x32_bf16 v[74:77], v[156:159], v[218:221], v[74:77]
	v_mfma_f32_16x16x32_bf16 v[118:121], v[160:163], v[190:193], v[118:121]
	v_mfma_f32_16x16x32_bf16 v[118:121], v[164:167], v[194:197], v[118:121]
	v_mfma_f32_16x16x32_bf16 v[114:117], v[168:171], v[190:193], v[114:117]
	v_mfma_f32_16x16x32_bf16 v[114:117], v[186:189], v[194:197], v[114:117]
	v_mfma_f32_16x16x32_bf16 v[102:105], v[160:163], v[198:201], v[102:105]
	v_mfma_f32_16x16x32_bf16 v[102:105], v[164:167], v[202:205], v[102:105]
	v_mfma_f32_16x16x32_bf16 v[98:101], v[168:171], v[198:201], v[98:101]
	v_mfma_f32_16x16x32_bf16 v[98:101], v[186:189], v[202:205], v[98:101]
	v_mfma_f32_16x16x32_bf16 v[86:89], v[160:163], v[206:209], v[86:89]
	v_mfma_f32_16x16x32_bf16 v[86:89], v[164:167], v[210:213], v[86:89]
	v_mfma_f32_16x16x32_bf16 v[82:85], v[168:171], v[206:209], v[82:85]
	v_mfma_f32_16x16x32_bf16 v[82:85], v[186:189], v[210:213], v[82:85]
	v_mfma_f32_16x16x32_bf16 v[70:73], v[160:163], v[214:217], v[70:73]
	v_mfma_f32_16x16x32_bf16 v[70:73], v[164:167], v[218:221], v[70:73]
	v_mfma_f32_16x16x32_bf16 v[66:69], v[168:171], v[214:217], v[66:69]
	v_mfma_f32_16x16x32_bf16 v[66:69], v[186:189], v[218:221], v[66:69]
	s_barrier
	s_add_i32 s62, s62, s49
	v_lshl_add_u64 v[172:173], vcc, 0, v[0:1]
	s_mov_b32 m0, s62
	ds_read_b128 v[190:193], v184 offset:16384
	ds_read_b128 v[194:197], v184 offset:17408
	ds_read_b128 v[198:201], v184 offset:18432
	ds_read_b128 v[202:205], v184 offset:19456
	ds_read_b128 v[206:209], v184 offset:20480
	ds_read_b128 v[210:213], v184 offset:21504
	ds_read_b128 v[214:217], v184 offset:22528
	ds_read_b128 v[218:221], v184 offset:23552
	global_load_lds_dwordx4 v[172:173], off
	s_add_i32 m0, s62, 0x2000
	v_lshl_add_u64 v[222:223], vcc, 0, v[142:143]
	s_add_u32 vcc_lo, vcc_lo, s96
	s_addc_u32 vcc_hi, vcc_hi, 0
	s_add_i32 s62, s63, s49
	global_load_lds_dwordx4 v[222:223], off
	v_lshl_add_u64 v[236:237], vcc, 0, v[0:1]
	s_mov_b32 m0, s62
	v_lshl_add_u64 v[238:239], vcc, 0, v[142:143]
	global_load_lds_dwordx4 v[236:237], off
	s_add_i32 m0, s62, 0x2000
	v_lshl_add_u64 v[240:241], s[30:31], 0, v[138:139]
	global_load_lds_dwordx4 v[238:239], off
	s_mov_b32 m0, s93
	v_lshl_add_u64 v[242:243], s[30:31], 0, v[140:141]
	global_load_lds_dwordx4 v[240:241], off
	s_mov_b32 m0, s88
	s_nop 0
	global_load_lds_dwordx4 v[242:243], off
	s_waitcnt vmcnt(8)
	s_waitcnt lgkmcnt(0)
	s_barrier
	s_waitcnt lgkmcnt(0)
	v_mfma_f32_16x16x32_bf16 v[62:65], v[130:133], v[190:193], v[62:65]
	v_mfma_f32_16x16x32_bf16 v[62:65], v[134:137], v[194:197], v[62:65]
	v_mfma_f32_16x16x32_bf16 v[58:61], v[152:155], v[190:193], v[58:61]
	v_mfma_f32_16x16x32_bf16 v[58:61], v[156:159], v[194:197], v[58:61]
	v_mfma_f32_16x16x32_bf16 v[46:49], v[130:133], v[198:201], v[46:49]
	v_mfma_f32_16x16x32_bf16 v[46:49], v[134:137], v[202:205], v[46:49]
	v_mfma_f32_16x16x32_bf16 v[42:45], v[152:155], v[198:201], v[42:45]
	v_mfma_f32_16x16x32_bf16 v[42:45], v[156:159], v[202:205], v[42:45]
	v_mfma_f32_16x16x32_bf16 v[30:33], v[130:133], v[206:209], v[30:33]
	v_mfma_f32_16x16x32_bf16 v[30:33], v[134:137], v[210:213], v[30:33]
	v_mfma_f32_16x16x32_bf16 v[26:29], v[152:155], v[206:209], v[26:29]
	v_mfma_f32_16x16x32_bf16 v[26:29], v[156:159], v[210:213], v[26:29]
	v_mfma_f32_16x16x32_bf16 v[14:17], v[130:133], v[214:217], v[14:17]
	v_mfma_f32_16x16x32_bf16 v[14:17], v[134:137], v[218:221], v[14:17]
	v_mfma_f32_16x16x32_bf16 v[10:13], v[152:155], v[214:217], v[10:13]
	v_mfma_f32_16x16x32_bf16 v[10:13], v[156:159], v[218:221], v[10:13]
	v_mfma_f32_16x16x32_bf16 v[54:57], v[160:163], v[190:193], v[54:57]
	v_mfma_f32_16x16x32_bf16 v[54:57], v[164:167], v[194:197], v[54:57]
	v_mfma_f32_16x16x32_bf16 v[50:53], v[168:171], v[190:193], v[50:53]
	v_mfma_f32_16x16x32_bf16 v[50:53], v[186:189], v[194:197], v[50:53]
	v_mfma_f32_16x16x32_bf16 v[38:41], v[160:163], v[198:201], v[38:41]
	v_mfma_f32_16x16x32_bf16 v[38:41], v[164:167], v[202:205], v[38:41]
	v_mfma_f32_16x16x32_bf16 v[34:37], v[168:171], v[198:201], v[34:37]
	v_mfma_f32_16x16x32_bf16 v[34:37], v[186:189], v[202:205], v[34:37]
	v_mfma_f32_16x16x32_bf16 v[22:25], v[160:163], v[206:209], v[22:25]
	v_mfma_f32_16x16x32_bf16 v[22:25], v[164:167], v[210:213], v[22:25]
	v_mfma_f32_16x16x32_bf16 v[18:21], v[168:171], v[206:209], v[18:21]
	v_mfma_f32_16x16x32_bf16 v[18:21], v[186:189], v[210:213], v[18:21]
	v_mfma_f32_16x16x32_bf16 v[6:9], v[160:163], v[214:217], v[6:9]
	v_mfma_f32_16x16x32_bf16 v[6:9], v[164:167], v[218:221], v[6:9]
	v_mfma_f32_16x16x32_bf16 v[2:5], v[168:171], v[214:217], v[2:5]
	v_mfma_f32_16x16x32_bf16 v[2:5], v[186:189], v[218:221], v[2:5]
	s_barrier
	s_add_i32 s62, 0, 0x18000
	v_add_u32_e32 v145, s62, v175
	s_add_i32 s63, 0, 0x1c000
	ds_read_b128 v[130:133], v145
	ds_read_b128 v[134:137], v145 offset:1024
	ds_read_b128 v[152:155], v145 offset:2048
	ds_read_b128 v[156:159], v145 offset:3072
	v_add_u32_e32 v145, s63, v175
	ds_read_b128 v[160:163], v145
	ds_read_b128 v[164:167], v145 offset:1024
	ds_read_b128 v[168:171], v145 offset:2048
	ds_read_b128 v[186:189], v145 offset:3072
	s_add_u32 s30, s30, s96
	s_addc_u32 s31, s31, 0
	s_mov_b32 m0, s89
	v_lshl_add_u64 v[244:245], s[30:31], 0, v[138:139]
	ds_read_b128 v[190:193], v184 offset:32768
	ds_read_b128 v[194:197], v184 offset:33792
	ds_read_b128 v[198:201], v184 offset:34816
	ds_read_b128 v[202:205], v184 offset:35840
	ds_read_b128 v[206:209], v184 offset:36864
	ds_read_b128 v[210:213], v184 offset:37888
	ds_read_b128 v[214:217], v184 offset:38912
	ds_read_b128 v[218:221], v184 offset:39936
	global_load_lds_dwordx4 v[244:245], off
	v_lshl_add_u64 v[244:245], s[30:31], 0, v[140:141]
	s_mov_b32 m0, s52
	s_nop 0
	global_load_lds_dwordx4 v[244:245], off
	s_waitcnt vmcnt(8)
	s_waitcnt lgkmcnt(0)
	s_barrier
	s_waitcnt lgkmcnt(0)
	v_mfma_f32_16x16x32_bf16 v[126:129], v[130:133], v[190:193], v[126:129]
	v_mfma_f32_16x16x32_bf16 v[126:129], v[134:137], v[194:197], v[126:129]
	v_mfma_f32_16x16x32_bf16 v[122:125], v[152:155], v[190:193], v[122:125]
	v_mfma_f32_16x16x32_bf16 v[122:125], v[156:159], v[194:197], v[122:125]
	v_mfma_f32_16x16x32_bf16 v[110:113], v[130:133], v[198:201], v[110:113]
	v_mfma_f32_16x16x32_bf16 v[110:113], v[134:137], v[202:205], v[110:113]
	v_mfma_f32_16x16x32_bf16 v[106:109], v[152:155], v[198:201], v[106:109]
	v_mfma_f32_16x16x32_bf16 v[106:109], v[156:159], v[202:205], v[106:109]
	v_mfma_f32_16x16x32_bf16 v[94:97], v[130:133], v[206:209], v[94:97]
	v_mfma_f32_16x16x32_bf16 v[94:97], v[134:137], v[210:213], v[94:97]
	v_mfma_f32_16x16x32_bf16 v[90:93], v[152:155], v[206:209], v[90:93]
	v_mfma_f32_16x16x32_bf16 v[90:93], v[156:159], v[210:213], v[90:93]
	v_mfma_f32_16x16x32_bf16 v[78:81], v[130:133], v[214:217], v[78:81]
	v_mfma_f32_16x16x32_bf16 v[78:81], v[134:137], v[218:221], v[78:81]
	v_mfma_f32_16x16x32_bf16 v[74:77], v[152:155], v[214:217], v[74:77]
	v_mfma_f32_16x16x32_bf16 v[74:77], v[156:159], v[218:221], v[74:77]
	v_mfma_f32_16x16x32_bf16 v[118:121], v[160:163], v[190:193], v[118:121]
	v_mfma_f32_16x16x32_bf16 v[118:121], v[164:167], v[194:197], v[118:121]
	v_mfma_f32_16x16x32_bf16 v[114:117], v[168:171], v[190:193], v[114:117]
	v_mfma_f32_16x16x32_bf16 v[114:117], v[186:189], v[194:197], v[114:117]
	v_mfma_f32_16x16x32_bf16 v[102:105], v[160:163], v[198:201], v[102:105]
	v_mfma_f32_16x16x32_bf16 v[102:105], v[164:167], v[202:205], v[102:105]
	v_mfma_f32_16x16x32_bf16 v[98:101], v[168:171], v[198:201], v[98:101]
	v_mfma_f32_16x16x32_bf16 v[98:101], v[186:189], v[202:205], v[98:101]
	v_mfma_f32_16x16x32_bf16 v[86:89], v[160:163], v[206:209], v[86:89]
	v_mfma_f32_16x16x32_bf16 v[86:89], v[164:167], v[210:213], v[86:89]
	v_mfma_f32_16x16x32_bf16 v[82:85], v[168:171], v[206:209], v[82:85]
	v_mfma_f32_16x16x32_bf16 v[82:85], v[186:189], v[210:213], v[82:85]
	v_mfma_f32_16x16x32_bf16 v[70:73], v[160:163], v[214:217], v[70:73]
	v_mfma_f32_16x16x32_bf16 v[70:73], v[164:167], v[218:221], v[70:73]
	v_mfma_f32_16x16x32_bf16 v[66:69], v[168:171], v[214:217], v[66:69]
	v_mfma_f32_16x16x32_bf16 v[66:69], v[186:189], v[218:221], v[66:69]
	s_barrier
	s_add_i32 s30, s62, s49
	v_lshl_add_u64 v[172:173], v[172:173], 0, s[98:99]
	s_mov_b32 m0, s30
	ds_read_b128 v[190:193], v184 offset:49152
	ds_read_b128 v[194:197], v184 offset:50176
	ds_read_b128 v[198:201], v184 offset:51200
	ds_read_b128 v[202:205], v184 offset:52224
	ds_read_b128 v[206:209], v184 offset:53248
	ds_read_b128 v[210:213], v184 offset:54272
	ds_read_b128 v[214:217], v184 offset:55296
	ds_read_b128 v[218:221], v184 offset:56320
	global_load_lds_dwordx4 v[172:173], off
	v_lshl_add_u64 v[172:173], v[222:223], 0, s[98:99]
	s_add_i32 m0, s30, 0x2000
	s_add_i32 s30, s63, s49
	global_load_lds_dwordx4 v[172:173], off
	v_lshl_add_u64 v[172:173], v[236:237], 0, s[98:99]
	s_mov_b32 m0, s30
	s_nop 0
	global_load_lds_dwordx4 v[172:173], off
	v_lshl_add_u64 v[172:173], v[238:239], 0, s[98:99]
	s_add_i32 m0, s30, 0x2000
	s_nop 0
	global_load_lds_dwordx4 v[172:173], off
	v_lshl_add_u64 v[172:173], v[240:241], 0, s[98:99]
	s_mov_b32 m0, s95
	s_nop 0
	global_load_lds_dwordx4 v[172:173], off
	v_lshl_add_u64 v[172:173], v[242:243], 0, s[98:99]
	s_mov_b32 m0, s54
	s_nop 0
	global_load_lds_dwordx4 v[172:173], off
	s_waitcnt vmcnt(8)
	s_waitcnt lgkmcnt(0)
	s_barrier
	s_waitcnt lgkmcnt(0)
	v_mfma_f32_16x16x32_bf16 v[62:65], v[130:133], v[190:193], v[62:65]
	v_mfma_f32_16x16x32_bf16 v[62:65], v[134:137], v[194:197], v[62:65]
	v_mfma_f32_16x16x32_bf16 v[58:61], v[152:155], v[190:193], v[58:61]
	v_mfma_f32_16x16x32_bf16 v[58:61], v[156:159], v[194:197], v[58:61]
	v_mfma_f32_16x16x32_bf16 v[46:49], v[130:133], v[198:201], v[46:49]
	v_mfma_f32_16x16x32_bf16 v[46:49], v[134:137], v[202:205], v[46:49]
	v_mfma_f32_16x16x32_bf16 v[42:45], v[152:155], v[198:201], v[42:45]
	v_mfma_f32_16x16x32_bf16 v[42:45], v[156:159], v[202:205], v[42:45]
	v_mfma_f32_16x16x32_bf16 v[30:33], v[130:133], v[206:209], v[30:33]
	v_mfma_f32_16x16x32_bf16 v[30:33], v[134:137], v[210:213], v[30:33]
	v_mfma_f32_16x16x32_bf16 v[26:29], v[152:155], v[206:209], v[26:29]
	v_mfma_f32_16x16x32_bf16 v[26:29], v[156:159], v[210:213], v[26:29]
	v_mfma_f32_16x16x32_bf16 v[14:17], v[130:133], v[214:217], v[14:17]
	v_mfma_f32_16x16x32_bf16 v[14:17], v[134:137], v[218:221], v[14:17]
	v_mfma_f32_16x16x32_bf16 v[10:13], v[152:155], v[214:217], v[10:13]
	v_mfma_f32_16x16x32_bf16 v[10:13], v[156:159], v[218:221], v[10:13]
	v_mfma_f32_16x16x32_bf16 v[54:57], v[160:163], v[190:193], v[54:57]
	v_mfma_f32_16x16x32_bf16 v[54:57], v[164:167], v[194:197], v[54:57]
	v_mfma_f32_16x16x32_bf16 v[50:53], v[168:171], v[190:193], v[50:53]
	v_mfma_f32_16x16x32_bf16 v[50:53], v[186:189], v[194:197], v[50:53]
	v_mfma_f32_16x16x32_bf16 v[38:41], v[160:163], v[198:201], v[38:41]
	v_mfma_f32_16x16x32_bf16 v[38:41], v[164:167], v[202:205], v[38:41]
	v_mfma_f32_16x16x32_bf16 v[34:37], v[168:171], v[198:201], v[34:37]
	v_mfma_f32_16x16x32_bf16 v[34:37], v[186:189], v[202:205], v[34:37]
	v_mfma_f32_16x16x32_bf16 v[22:25], v[160:163], v[206:209], v[22:25]
	v_mfma_f32_16x16x32_bf16 v[22:25], v[164:167], v[210:213], v[22:25]
	v_mfma_f32_16x16x32_bf16 v[18:21], v[168:171], v[206:209], v[18:21]
	v_mfma_f32_16x16x32_bf16 v[18:21], v[186:189], v[210:213], v[18:21]
	v_mfma_f32_16x16x32_bf16 v[6:9], v[160:163], v[214:217], v[6:9]
	v_mfma_f32_16x16x32_bf16 v[6:9], v[164:167], v[218:221], v[6:9]
	v_mfma_f32_16x16x32_bf16 v[2:5], v[168:171], v[214:217], v[2:5]
	v_mfma_f32_16x16x32_bf16 v[2:5], v[186:189], v[218:221], v[2:5]
	s_barrier
	s_add_u32 s28, s28, 0x100
	s_addc_u32 s29, s29, 0
	s_add_u32 s23, s23, 0x100
	s_addc_u32 s40, s40, 0
	s_cmp_ge_i32 s41, s61
	s_mov_b32 s30, s41
	s_cbranch_scc0 .LBB0_217

.LBB0_373:
	s_ashr_i32 s17, s16, 31
	s_lshl_b64 s[20:21], s[16:17], 19
	s_add_u32 s20, s37, s20
	s_addc_u32 s21, s40, s21
	s_and_b64 s[22:23], s[18:19], exec
	s_cselect_b32 s17, s21, s29
	s_cselect_b32 s25, s20, s28
	s_ashr_i32 s15, s14, 31
	s_lshl_b64 s[22:23], s[14:15], 19
	s_add_u32 s22, s41, s22
	s_addc_u32 s23, s42, s23
	s_and_b64 s[38:39], s[18:19], exec
	s_cselect_b32 s15, s23, s31
	s_cselect_b32 s53, s22, s30
	s_add_u32 s28, s28, 0x40080
	s_addc_u32 s29, s29, 0
	s_add_u32 s54, s30, 0x100
	s_addc_u32 s55, s31, 0
	s_mov_b32 s56, -2
	s_add_u32 s30, s28, 0xfffc0080
	s_addc_u32 s31, s29, -1
	s_add_i32 s57, 0, 0x10000
	s_cmp_eq_u32 s56, 12
	s_cselect_b32 s39, s17, s31
	s_cselect_b32 s38, s25, s30
	s_cselect_b32 s31, s15, s55
	s_cselect_b32 s30, s53, s54
	s_add_i32 s60, 0, 0x14000
	v_add_u32_e32 v156, s57, v145
	v_add_u32_e32 v172, s60, v145
	ds_read_b128 v[140:143], v156
	ds_read_b128 v[148:151], v156 offset:1024
	ds_read_b128 v[152:155], v156 offset:2048
	ds_read_b128 v[156:159], v156 offset:3072
	ds_read_b128 v[160:163], v172
	ds_read_b128 v[164:167], v172 offset:1024
	ds_read_b128 v[168:171], v172 offset:2048
	ds_read_b128 v[172:175], v172 offset:3072
	v_lshl_add_u64 v[208:209], s[28:29], 0, v[136:137]
	s_add_i32 m0, s27, 0xc000
	ds_read_b128 v[176:179], v147
	ds_read_b128 v[180:183], v147 offset:1024
	ds_read_b128 v[184:187], v147 offset:2048
	ds_read_b128 v[188:191], v147 offset:3072
	ds_read_b128 v[192:195], v147 offset:4096
	ds_read_b128 v[196:199], v147 offset:5120
	ds_read_b128 v[200:203], v147 offset:6144
	ds_read_b128 v[204:207], v147 offset:7168
	global_load_lds_dwordx4 v[208:209], off
	v_lshl_add_u64 v[208:209], s[28:29], 0, v[138:139]
	s_add_i32 m0, s27, 0xe000
	s_nop 0
	global_load_lds_dwordx4 v[208:209], off
	s_waitcnt vmcnt(8)
	s_waitcnt lgkmcnt(0)
	s_barrier
	s_waitcnt lgkmcnt(0)
	v_mfma_f32_16x16x32_bf16 v[122:125], v[140:143], v[176:179], 0
	v_mfma_f32_16x16x32_bf16 v[122:125], v[148:151], v[180:183], v[122:125]
	v_mfma_f32_16x16x32_bf16 v[114:117], v[152:155], v[176:179], 0
	v_mfma_f32_16x16x32_bf16 v[114:117], v[156:159], v[180:183], v[114:117]
	v_mfma_f32_16x16x32_bf16 v[106:109], v[140:143], v[184:187], 0
	v_mfma_f32_16x16x32_bf16 v[106:109], v[148:151], v[188:191], v[106:109]
	v_mfma_f32_16x16x32_bf16 v[98:101], v[152:155], v[184:187], 0
	v_mfma_f32_16x16x32_bf16 v[98:101], v[156:159], v[188:191], v[98:101]
	v_mfma_f32_16x16x32_bf16 v[90:93], v[140:143], v[192:195], 0
	v_mfma_f32_16x16x32_bf16 v[90:93], v[148:151], v[196:199], v[90:93]
	v_mfma_f32_16x16x32_bf16 v[82:85], v[152:155], v[192:195], 0
	v_mfma_f32_16x16x32_bf16 v[82:85], v[156:159], v[196:199], v[82:85]
	v_mfma_f32_16x16x32_bf16 v[74:77], v[140:143], v[200:203], 0
	v_mfma_f32_16x16x32_bf16 v[74:77], v[148:151], v[204:207], v[74:77]
	v_mfma_f32_16x16x32_bf16 v[66:69], v[152:155], v[200:203], 0
	v_mfma_f32_16x16x32_bf16 v[66:69], v[156:159], v[204:207], v[66:69]
	v_mfma_f32_16x16x32_bf16 v[126:129], v[160:163], v[176:179], 0
	v_mfma_f32_16x16x32_bf16 v[126:129], v[164:167], v[180:183], v[126:129]
	v_mfma_f32_16x16x32_bf16 v[118:121], v[168:171], v[176:179], 0
	v_mfma_f32_16x16x32_bf16 v[118:121], v[172:175], v[180:183], v[118:121]
	v_mfma_f32_16x16x32_bf16 v[110:113], v[160:163], v[184:187], 0
	v_mfma_f32_16x16x32_bf16 v[110:113], v[164:167], v[188:191], v[110:113]
	v_mfma_f32_16x16x32_bf16 v[102:105], v[168:171], v[184:187], 0
	v_mfma_f32_16x16x32_bf16 v[102:105], v[172:175], v[188:191], v[102:105]
	v_mfma_f32_16x16x32_bf16 v[94:97], v[160:163], v[192:195], 0
	v_mfma_f32_16x16x32_bf16 v[94:97], v[164:167], v[196:199], v[94:97]
	v_mfma_f32_16x16x32_bf16 v[86:89], v[168:171], v[192:195], 0
	v_mfma_f32_16x16x32_bf16 v[86:89], v[172:175], v[196:199], v[86:89]
	v_mfma_f32_16x16x32_bf16 v[78:81], v[160:163], v[200:203], 0
	v_mfma_f32_16x16x32_bf16 v[78:81], v[164:167], v[204:207], v[78:81]
	v_mfma_f32_16x16x32_bf16 v[70:73], v[168:171], v[200:203], 0
	v_mfma_f32_16x16x32_bf16 v[70:73], v[172:175], v[204:207], v[70:73]
	s_barrier
	s_add_i32 s57, s57, s43
	v_lshl_add_u64 v[208:209], s[30:31], 0, v[0:1]
	s_mov_b32 m0, s57
	ds_read_b128 v[176:179], v147 offset:16384
	ds_read_b128 v[180:183], v147 offset:17408
	ds_read_b128 v[184:187], v147 offset:18432
	ds_read_b128 v[188:191], v147 offset:19456
	ds_read_b128 v[192:195], v147 offset:20480
	ds_read_b128 v[196:199], v147 offset:21504
	ds_read_b128 v[200:203], v147 offset:22528
	ds_read_b128 v[204:207], v147 offset:23552
	global_load_lds_dwordx4 v[208:209], off
	s_add_i32 m0, s57, 0x2000
	s_add_u32 s58, s30, 0x40000
	v_lshl_add_u64 v[210:211], s[30:31], 0, v[134:135]
	s_addc_u32 s59, s31, 0
	s_add_i32 s57, s60, s43
	global_load_lds_dwordx4 v[210:211], off
	v_lshl_add_u64 v[212:213], s[58:59], 0, v[0:1]
	s_mov_b32 m0, s57
	v_lshl_add_u64 v[214:215], s[38:39], 0, v[132:133]
	global_load_lds_dwordx4 v[212:213], off
	v_lshl_add_u64 v[212:213], s[58:59], 0, v[134:135]
	s_add_i32 m0, s57, 0x2000
	s_nop 0
	global_load_lds_dwordx4 v[212:213], off
	v_lshl_add_u64 v[212:213], s[38:39], 0, v[130:131]
	s_mov_b32 m0, s27
	s_nop 0
	global_load_lds_dwordx4 v[212:213], off
	s_mov_b32 m0, s44
	s_nop 0
	global_load_lds_dwordx4 v[214:215], off
	s_waitcnt vmcnt(8)
	s_waitcnt lgkmcnt(0)
	s_barrier
	s_waitcnt lgkmcnt(0)
	v_mfma_f32_16x16x32_bf16 v[58:61], v[140:143], v[176:179], 0
	v_mfma_f32_16x16x32_bf16 v[58:61], v[148:151], v[180:183], v[58:61]
	v_mfma_f32_16x16x32_bf16 v[50:53], v[152:155], v[176:179], 0
	v_mfma_f32_16x16x32_bf16 v[50:53], v[156:159], v[180:183], v[50:53]
	v_mfma_f32_16x16x32_bf16 v[42:45], v[140:143], v[184:187], 0
	v_mfma_f32_16x16x32_bf16 v[42:45], v[148:151], v[188:191], v[42:45]
	v_mfma_f32_16x16x32_bf16 v[34:37], v[152:155], v[184:187], 0
	v_mfma_f32_16x16x32_bf16 v[34:37], v[156:159], v[188:191], v[34:37]
	v_mfma_f32_16x16x32_bf16 v[26:29], v[140:143], v[192:195], 0
	v_mfma_f32_16x16x32_bf16 v[26:29], v[148:151], v[196:199], v[26:29]
	v_mfma_f32_16x16x32_bf16 v[18:21], v[152:155], v[192:195], 0
	v_mfma_f32_16x16x32_bf16 v[18:21], v[156:159], v[196:199], v[18:21]
	v_mfma_f32_16x16x32_bf16 v[10:13], v[140:143], v[200:203], 0
	v_mfma_f32_16x16x32_bf16 v[10:13], v[148:151], v[204:207], v[10:13]
	v_mfma_f32_16x16x32_bf16 v[6:9], v[152:155], v[200:203], 0
	v_mfma_f32_16x16x32_bf16 v[6:9], v[156:159], v[204:207], v[6:9]
	v_mfma_f32_16x16x32_bf16 v[62:65], v[160:163], v[176:179], 0
	v_mfma_f32_16x16x32_bf16 v[62:65], v[164:167], v[180:183], v[62:65]
	v_mfma_f32_16x16x32_bf16 v[54:57], v[168:171], v[176:179], 0
	v_mfma_f32_16x16x32_bf16 v[54:57], v[172:175], v[180:183], v[54:57]
	v_mfma_f32_16x16x32_bf16 v[46:49], v[160:163], v[184:187], 0
	v_mfma_f32_16x16x32_bf16 v[46:49], v[164:167], v[188:191], v[46:49]
	v_mfma_f32_16x16x32_bf16 v[38:41], v[168:171], v[184:187], 0
	v_mfma_f32_16x16x32_bf16 v[38:41], v[172:175], v[188:191], v[38:41]
	v_mfma_f32_16x16x32_bf16 v[30:33], v[160:163], v[192:195], 0
	v_mfma_f32_16x16x32_bf16 v[30:33], v[164:167], v[196:199], v[30:33]
	v_mfma_f32_16x16x32_bf16 v[22:25], v[168:171], v[192:195], 0
	v_mfma_f32_16x16x32_bf16 v[22:25], v[172:175], v[196:199], v[22:25]
	v_mfma_f32_16x16x32_bf16 v[14:17], v[160:163], v[200:203], 0
	v_mfma_f32_16x16x32_bf16 v[14:17], v[164:167], v[204:207], v[14:17]
	v_mfma_f32_16x16x32_bf16 v[2:5], v[168:171], v[200:203], 0
	v_mfma_f32_16x16x32_bf16 v[2:5], v[172:175], v[204:207], v[2:5]
	s_barrier
	s_add_i32 s57, 0, 0x18000
	s_add_i32 s58, 0, 0x1c000
	v_add_u32_e32 v156, s57, v145
	v_add_u32_e32 v172, s58, v145
	ds_read_b128 v[140:143], v156
	ds_read_b128 v[148:151], v156 offset:1024
	ds_read_b128 v[152:155], v156 offset:2048
	ds_read_b128 v[156:159], v156 offset:3072
	ds_read_b128 v[160:163], v172
	ds_read_b128 v[164:167], v172 offset:1024
	ds_read_b128 v[168:171], v172 offset:2048
	ds_read_b128 v[172:175], v172 offset:3072
	s_add_u32 s38, s38, 0x40000
	s_addc_u32 s39, s39, 0
	s_mov_b32 m0, s45
	v_lshl_add_u64 v[216:217], s[38:39], 0, v[130:131]
	ds_read_b128 v[176:179], v147 offset:32768
	ds_read_b128 v[180:183], v147 offset:33792
	ds_read_b128 v[184:187], v147 offset:34816
	ds_read_b128 v[188:191], v147 offset:35840
	ds_read_b128 v[192:195], v147 offset:36864
	ds_read_b128 v[196:199], v147 offset:37888
	ds_read_b128 v[200:203], v147 offset:38912
	ds_read_b128 v[204:207], v147 offset:39936
	global_load_lds_dwordx4 v[216:217], off
	v_lshl_add_u64 v[216:217], s[38:39], 0, v[132:133]
	s_mov_b32 m0, s47
	s_nop 0
	global_load_lds_dwordx4 v[216:217], off
	s_waitcnt vmcnt(8)
	s_waitcnt lgkmcnt(0)
	s_barrier
	s_waitcnt lgkmcnt(0)
	v_mfma_f32_16x16x32_bf16 v[122:125], v[140:143], v[176:179], v[122:125]
	v_mfma_f32_16x16x32_bf16 v[122:125], v[148:151], v[180:183], v[122:125]
	v_mfma_f32_16x16x32_bf16 v[114:117], v[152:155], v[176:179], v[114:117]
	v_mfma_f32_16x16x32_bf16 v[114:117], v[156:159], v[180:183], v[114:117]
	v_mfma_f32_16x16x32_bf16 v[106:109], v[140:143], v[184:187], v[106:109]
	v_mfma_f32_16x16x32_bf16 v[106:109], v[148:151], v[188:191], v[106:109]
	v_mfma_f32_16x16x32_bf16 v[98:101], v[152:155], v[184:187], v[98:101]
	v_mfma_f32_16x16x32_bf16 v[98:101], v[156:159], v[188:191], v[98:101]
	v_mfma_f32_16x16x32_bf16 v[90:93], v[140:143], v[192:195], v[90:93]
	v_mfma_f32_16x16x32_bf16 v[90:93], v[148:151], v[196:199], v[90:93]
	v_mfma_f32_16x16x32_bf16 v[82:85], v[152:155], v[192:195], v[82:85]
	v_mfma_f32_16x16x32_bf16 v[82:85], v[156:159], v[196:199], v[82:85]
	v_mfma_f32_16x16x32_bf16 v[74:77], v[140:143], v[200:203], v[74:77]
	v_mfma_f32_16x16x32_bf16 v[74:77], v[148:151], v[204:207], v[74:77]
	v_mfma_f32_16x16x32_bf16 v[66:69], v[152:155], v[200:203], v[66:69]
	v_mfma_f32_16x16x32_bf16 v[66:69], v[156:159], v[204:207], v[66:69]
	v_mfma_f32_16x16x32_bf16 v[126:129], v[160:163], v[176:179], v[126:129]
	v_mfma_f32_16x16x32_bf16 v[126:129], v[164:167], v[180:183], v[126:129]
	v_mfma_f32_16x16x32_bf16 v[118:121], v[168:171], v[176:179], v[118:121]
	v_mfma_f32_16x16x32_bf16 v[118:121], v[172:175], v[180:183], v[118:121]
	v_mfma_f32_16x16x32_bf16 v[110:113], v[160:163], v[184:187], v[110:113]
	v_mfma_f32_16x16x32_bf16 v[110:113], v[164:167], v[188:191], v[110:113]
	v_mfma_f32_16x16x32_bf16 v[102:105], v[168:171], v[184:187], v[102:105]
	v_mfma_f32_16x16x32_bf16 v[102:105], v[172:175], v[188:191], v[102:105]
	v_mfma_f32_16x16x32_bf16 v[94:97], v[160:163], v[192:195], v[94:97]
	v_mfma_f32_16x16x32_bf16 v[94:97], v[164:167], v[196:199], v[94:97]
	v_mfma_f32_16x16x32_bf16 v[86:89], v[168:171], v[192:195], v[86:89]
	v_mfma_f32_16x16x32_bf16 v[86:89], v[172:175], v[196:199], v[86:89]
	v_mfma_f32_16x16x32_bf16 v[78:81], v[160:163], v[200:203], v[78:81]
	v_mfma_f32_16x16x32_bf16 v[78:81], v[164:167], v[204:207], v[78:81]
	v_mfma_f32_16x16x32_bf16 v[70:73], v[168:171], v[200:203], v[70:73]
	v_mfma_f32_16x16x32_bf16 v[70:73], v[172:175], v[204:207], v[70:73]
	s_barrier
	s_add_i32 s38, s57, s43
	v_lshl_add_u64 v[208:209], v[208:209], 0, s[98:99]
	s_mov_b32 m0, s38
	ds_read_b128 v[176:179], v147 offset:49152
	ds_read_b128 v[180:183], v147 offset:50176
	ds_read_b128 v[184:187], v147 offset:51200
	ds_read_b128 v[188:191], v147 offset:52224
	ds_read_b128 v[192:195], v147 offset:53248
	ds_read_b128 v[196:199], v147 offset:54272
	ds_read_b128 v[200:203], v147 offset:55296
	ds_read_b128 v[204:207], v147 offset:56320
	global_load_lds_dwordx4 v[208:209], off
	s_add_i32 m0, s38, 0x2000
	s_add_u32 s30, s30, 0x40080
	v_lshl_add_u64 v[208:209], v[210:211], 0, s[98:99]
	s_addc_u32 s31, s31, 0
	s_add_i32 s38, s58, s43
	global_load_lds_dwordx4 v[208:209], off
	v_lshl_add_u64 v[208:209], s[30:31], 0, v[0:1]
	s_mov_b32 m0, s38
	s_nop 0
	global_load_lds_dwordx4 v[208:209], off
	v_lshl_add_u64 v[208:209], s[30:31], 0, v[134:135]
	s_add_i32 m0, s38, 0x2000
	s_nop 0
	global_load_lds_dwordx4 v[208:209], off
	v_lshl_add_u64 v[208:209], v[212:213], 0, s[98:99]
	s_mov_b32 m0, s49
	s_nop 0
	global_load_lds_dwordx4 v[208:209], off
	v_lshl_add_u64 v[208:209], v[214:215], 0, s[98:99]
	s_mov_b32 m0, s51
	s_nop 0
	global_load_lds_dwordx4 v[208:209], off
	s_waitcnt vmcnt(8)
	s_waitcnt lgkmcnt(0)
	s_barrier
	s_waitcnt lgkmcnt(0)
	v_mfma_f32_16x16x32_bf16 v[58:61], v[140:143], v[176:179], v[58:61]
	v_mfma_f32_16x16x32_bf16 v[58:61], v[148:151], v[180:183], v[58:61]
	v_mfma_f32_16x16x32_bf16 v[50:53], v[152:155], v[176:179], v[50:53]
	v_mfma_f32_16x16x32_bf16 v[50:53], v[156:159], v[180:183], v[50:53]
	v_mfma_f32_16x16x32_bf16 v[42:45], v[140:143], v[184:187], v[42:45]
	v_mfma_f32_16x16x32_bf16 v[42:45], v[148:151], v[188:191], v[42:45]
	v_mfma_f32_16x16x32_bf16 v[34:37], v[152:155], v[184:187], v[34:37]
	v_mfma_f32_16x16x32_bf16 v[34:37], v[156:159], v[188:191], v[34:37]
	v_mfma_f32_16x16x32_bf16 v[26:29], v[140:143], v[192:195], v[26:29]
	v_mfma_f32_16x16x32_bf16 v[26:29], v[148:151], v[196:199], v[26:29]
	v_mfma_f32_16x16x32_bf16 v[18:21], v[152:155], v[192:195], v[18:21]
	v_mfma_f32_16x16x32_bf16 v[18:21], v[156:159], v[196:199], v[18:21]
	v_mfma_f32_16x16x32_bf16 v[10:13], v[140:143], v[200:203], v[10:13]
	v_mfma_f32_16x16x32_bf16 v[10:13], v[148:151], v[204:207], v[10:13]
	v_mfma_f32_16x16x32_bf16 v[6:9], v[152:155], v[200:203], v[6:9]
	v_mfma_f32_16x16x32_bf16 v[6:9], v[156:159], v[204:207], v[6:9]
	v_mfma_f32_16x16x32_bf16 v[62:65], v[160:163], v[176:179], v[62:65]
	v_mfma_f32_16x16x32_bf16 v[62:65], v[164:167], v[180:183], v[62:65]
	v_mfma_f32_16x16x32_bf16 v[54:57], v[168:171], v[176:179], v[54:57]
	v_mfma_f32_16x16x32_bf16 v[54:57], v[172:175], v[180:183], v[54:57]
	v_mfma_f32_16x16x32_bf16 v[46:49], v[160:163], v[184:187], v[46:49]
	v_mfma_f32_16x16x32_bf16 v[46:49], v[164:167], v[188:191], v[46:49]
	v_mfma_f32_16x16x32_bf16 v[38:41], v[168:171], v[184:187], v[38:41]
	v_mfma_f32_16x16x32_bf16 v[38:41], v[172:175], v[188:191], v[38:41]
	v_mfma_f32_16x16x32_bf16 v[30:33], v[160:163], v[192:195], v[30:33]
	v_mfma_f32_16x16x32_bf16 v[30:33], v[164:167], v[196:199], v[30:33]
	v_mfma_f32_16x16x32_bf16 v[22:25], v[168:171], v[192:195], v[22:25]
	v_mfma_f32_16x16x32_bf16 v[22:25], v[172:175], v[196:199], v[22:25]
	v_mfma_f32_16x16x32_bf16 v[14:17], v[160:163], v[200:203], v[14:17]
	v_mfma_f32_16x16x32_bf16 v[14:17], v[164:167], v[204:207], v[14:17]
	v_mfma_f32_16x16x32_bf16 v[2:5], v[168:171], v[200:203], v[2:5]
	v_mfma_f32_16x16x32_bf16 v[2:5], v[172:175], v[204:207], v[2:5]
	s_barrier
	s_add_i32 s56, s56, 2
	s_add_u32 s28, s28, 0x100
	s_addc_u32 s29, s29, 0
	s_add_u32 s54, s54, 0x100
	s_addc_u32 s55, s55, 0
	s_cmp_gt_u32 s56, 13
	s_cbranch_scc1 .Lpeel_done_374
.LBB0_374:
	s_add_u32 s30, s28, 0xfffc0080
	s_addc_u32 s31, s29, -1
	s_add_i32 s57, 0, 0x10000
	s_cmp_eq_u32 s56, 12
	s_cselect_b32 s39, s17, s31
	s_cselect_b32 s38, s25, s30
	s_cselect_b32 s31, s15, s55
	s_cselect_b32 s30, s53, s54
	s_add_i32 s60, 0, 0x14000
	v_add_u32_e32 v156, s57, v145
	v_add_u32_e32 v172, s60, v145
	ds_read_b128 v[140:143], v156
	ds_read_b128 v[148:151], v156 offset:1024
	ds_read_b128 v[152:155], v156 offset:2048
	ds_read_b128 v[156:159], v156 offset:3072
	ds_read_b128 v[160:163], v172
	ds_read_b128 v[164:167], v172 offset:1024
	ds_read_b128 v[168:171], v172 offset:2048
	ds_read_b128 v[172:175], v172 offset:3072
	v_lshl_add_u64 v[208:209], s[28:29], 0, v[136:137]
	s_add_i32 m0, s27, 0xc000
	ds_read_b128 v[176:179], v147
	ds_read_b128 v[180:183], v147 offset:1024
	ds_read_b128 v[184:187], v147 offset:2048
	ds_read_b128 v[188:191], v147 offset:3072
	ds_read_b128 v[192:195], v147 offset:4096
	ds_read_b128 v[196:199], v147 offset:5120
	ds_read_b128 v[200:203], v147 offset:6144
	ds_read_b128 v[204:207], v147 offset:7168
	global_load_lds_dwordx4 v[208:209], off
	v_lshl_add_u64 v[208:209], s[28:29], 0, v[138:139]
	s_add_i32 m0, s27, 0xe000
	s_nop 0
	global_load_lds_dwordx4 v[208:209], off
	s_waitcnt vmcnt(8)
	s_waitcnt lgkmcnt(0)
	s_barrier
	s_waitcnt lgkmcnt(0)
	v_mfma_f32_16x16x32_bf16 v[122:125], v[140:143], v[176:179], v[122:125]
	v_mfma_f32_16x16x32_bf16 v[122:125], v[148:151], v[180:183], v[122:125]
	v_mfma_f32_16x16x32_bf16 v[114:117], v[152:155], v[176:179], v[114:117]
	v_mfma_f32_16x16x32_bf16 v[114:117], v[156:159], v[180:183], v[114:117]
	v_mfma_f32_16x16x32_bf16 v[106:109], v[140:143], v[184:187], v[106:109]
	v_mfma_f32_16x16x32_bf16 v[106:109], v[148:151], v[188:191], v[106:109]
	v_mfma_f32_16x16x32_bf16 v[98:101], v[152:155], v[184:187], v[98:101]
	v_mfma_f32_16x16x32_bf16 v[98:101], v[156:159], v[188:191], v[98:101]
	v_mfma_f32_16x16x32_bf16 v[90:93], v[140:143], v[192:195], v[90:93]
	v_mfma_f32_16x16x32_bf16 v[90:93], v[148:151], v[196:199], v[90:93]
	v_mfma_f32_16x16x32_bf16 v[82:85], v[152:155], v[192:195], v[82:85]
	v_mfma_f32_16x16x32_bf16 v[82:85], v[156:159], v[196:199], v[82:85]
	v_mfma_f32_16x16x32_bf16 v[74:77], v[140:143], v[200:203], v[74:77]
	v_mfma_f32_16x16x32_bf16 v[74:77], v[148:151], v[204:207], v[74:77]
	v_mfma_f32_16x16x32_bf16 v[66:69], v[152:155], v[200:203], v[66:69]
	v_mfma_f32_16x16x32_bf16 v[66:69], v[156:159], v[204:207], v[66:69]
	v_mfma_f32_16x16x32_bf16 v[126:129], v[160:163], v[176:179], v[126:129]
	v_mfma_f32_16x16x32_bf16 v[126:129], v[164:167], v[180:183], v[126:129]
	v_mfma_f32_16x16x32_bf16 v[118:121], v[168:171], v[176:179], v[118:121]
	v_mfma_f32_16x16x32_bf16 v[118:121], v[172:175], v[180:183], v[118:121]
	v_mfma_f32_16x16x32_bf16 v[110:113], v[160:163], v[184:187], v[110:113]
	v_mfma_f32_16x16x32_bf16 v[110:113], v[164:167], v[188:191], v[110:113]
	v_mfma_f32_16x16x32_bf16 v[102:105], v[168:171], v[184:187], v[102:105]
	v_mfma_f32_16x16x32_bf16 v[102:105], v[172:175], v[188:191], v[102:105]
	v_mfma_f32_16x16x32_bf16 v[94:97], v[160:163], v[192:195], v[94:97]
	v_mfma_f32_16x16x32_bf16 v[94:97], v[164:167], v[196:199], v[94:97]
	v_mfma_f32_16x16x32_bf16 v[86:89], v[168:171], v[192:195], v[86:89]
	v_mfma_f32_16x16x32_bf16 v[86:89], v[172:175], v[196:199], v[86:89]
	v_mfma_f32_16x16x32_bf16 v[78:81], v[160:163], v[200:203], v[78:81]
	v_mfma_f32_16x16x32_bf16 v[78:81], v[164:167], v[204:207], v[78:81]
	v_mfma_f32_16x16x32_bf16 v[70:73], v[168:171], v[200:203], v[70:73]
	v_mfma_f32_16x16x32_bf16 v[70:73], v[172:175], v[204:207], v[70:73]
	s_barrier
	s_add_i32 s57, s57, s43
	v_lshl_add_u64 v[208:209], s[30:31], 0, v[0:1]
	s_mov_b32 m0, s57
	ds_read_b128 v[176:179], v147 offset:16384
	ds_read_b128 v[180:183], v147 offset:17408
	ds_read_b128 v[184:187], v147 offset:18432
	ds_read_b128 v[188:191], v147 offset:19456
	ds_read_b128 v[192:195], v147 offset:20480
	ds_read_b128 v[196:199], v147 offset:21504
	ds_read_b128 v[200:203], v147 offset:22528
	ds_read_b128 v[204:207], v147 offset:23552
	global_load_lds_dwordx4 v[208:209], off
	s_add_i32 m0, s57, 0x2000
	s_add_u32 s58, s30, 0x40000
	v_lshl_add_u64 v[210:211], s[30:31], 0, v[134:135]
	s_addc_u32 s59, s31, 0
	s_add_i32 s57, s60, s43
	global_load_lds_dwordx4 v[210:211], off
	v_lshl_add_u64 v[212:213], s[58:59], 0, v[0:1]
	s_mov_b32 m0, s57
	v_lshl_add_u64 v[214:215], s[38:39], 0, v[132:133]
	global_load_lds_dwordx4 v[212:213], off
	v_lshl_add_u64 v[212:213], s[58:59], 0, v[134:135]
	s_add_i32 m0, s57, 0x2000
	s_nop 0
	global_load_lds_dwordx4 v[212:213], off
	v_lshl_add_u64 v[212:213], s[38:39], 0, v[130:131]
	s_mov_b32 m0, s27
	s_nop 0
	global_load_lds_dwordx4 v[212:213], off
	s_mov_b32 m0, s44
	s_nop 0
	global_load_lds_dwordx4 v[214:215], off
	s_waitcnt vmcnt(8)
	s_waitcnt lgkmcnt(0)
	s_barrier
	s_waitcnt lgkmcnt(0)
	v_mfma_f32_16x16x32_bf16 v[58:61], v[140:143], v[176:179], v[58:61]
	v_mfma_f32_16x16x32_bf16 v[58:61], v[148:151], v[180:183], v[58:61]
	v_mfma_f32_16x16x32_bf16 v[50:53], v[152:155], v[176:179], v[50:53]
	v_mfma_f32_16x16x32_bf16 v[50:53], v[156:159], v[180:183], v[50:53]
	v_mfma_f32_16x16x32_bf16 v[42:45], v[140:143], v[184:187], v[42:45]
	v_mfma_f32_16x16x32_bf16 v[42:45], v[148:151], v[188:191], v[42:45]
	v_mfma_f32_16x16x32_bf16 v[34:37], v[152:155], v[184:187], v[34:37]
	v_mfma_f32_16x16x32_bf16 v[34:37], v[156:159], v[188:191], v[34:37]
	v_mfma_f32_16x16x32_bf16 v[26:29], v[140:143], v[192:195], v[26:29]
	v_mfma_f32_16x16x32_bf16 v[26:29], v[148:151], v[196:199], v[26:29]
	v_mfma_f32_16x16x32_bf16 v[18:21], v[152:155], v[192:195], v[18:21]
	v_mfma_f32_16x16x32_bf16 v[18:21], v[156:159], v[196:199], v[18:21]
	v_mfma_f32_16x16x32_bf16 v[10:13], v[140:143], v[200:203], v[10:13]
	v_mfma_f32_16x16x32_bf16 v[10:13], v[148:151], v[204:207], v[10:13]
	v_mfma_f32_16x16x32_bf16 v[6:9], v[152:155], v[200:203], v[6:9]
	v_mfma_f32_16x16x32_bf16 v[6:9], v[156:159], v[204:207], v[6:9]
	v_mfma_f32_16x16x32_bf16 v[62:65], v[160:163], v[176:179], v[62:65]
	v_mfma_f32_16x16x32_bf16 v[62:65], v[164:167], v[180:183], v[62:65]
	v_mfma_f32_16x16x32_bf16 v[54:57], v[168:171], v[176:179], v[54:57]
	v_mfma_f32_16x16x32_bf16 v[54:57], v[172:175], v[180:183], v[54:57]
	v_mfma_f32_16x16x32_bf16 v[46:49], v[160:163], v[184:187], v[46:49]
	v_mfma_f32_16x16x32_bf16 v[46:49], v[164:167], v[188:191], v[46:49]
	v_mfma_f32_16x16x32_bf16 v[38:41], v[168:171], v[184:187], v[38:41]
	v_mfma_f32_16x16x32_bf16 v[38:41], v[172:175], v[188:191], v[38:41]
	v_mfma_f32_16x16x32_bf16 v[30:33], v[160:163], v[192:195], v[30:33]
	v_mfma_f32_16x16x32_bf16 v[30:33], v[164:167], v[196:199], v[30:33]
	v_mfma_f32_16x16x32_bf16 v[22:25], v[168:171], v[192:195], v[22:25]
	v_mfma_f32_16x16x32_bf16 v[22:25], v[172:175], v[196:199], v[22:25]
	v_mfma_f32_16x16x32_bf16 v[14:17], v[160:163], v[200:203], v[14:17]
	v_mfma_f32_16x16x32_bf16 v[14:17], v[164:167], v[204:207], v[14:17]
	v_mfma_f32_16x16x32_bf16 v[2:5], v[168:171], v[200:203], v[2:5]
	v_mfma_f32_16x16x32_bf16 v[2:5], v[172:175], v[204:207], v[2:5]
	s_barrier
	s_add_i32 s57, 0, 0x18000
	s_add_i32 s58, 0, 0x1c000
	v_add_u32_e32 v156, s57, v145
	v_add_u32_e32 v172, s58, v145
	ds_read_b128 v[140:143], v156
	ds_read_b128 v[148:151], v156 offset:1024
	ds_read_b128 v[152:155], v156 offset:2048
	ds_read_b128 v[156:159], v156 offset:3072
	ds_read_b128 v[160:163], v172
	ds_read_b128 v[164:167], v172 offset:1024
	ds_read_b128 v[168:171], v172 offset:2048
	ds_read_b128 v[172:175], v172 offset:3072
	s_add_u32 s38, s38, 0x40000
	s_addc_u32 s39, s39, 0
	s_mov_b32 m0, s45
	v_lshl_add_u64 v[216:217], s[38:39], 0, v[130:131]
	ds_read_b128 v[176:179], v147 offset:32768
	ds_read_b128 v[180:183], v147 offset:33792
	ds_read_b128 v[184:187], v147 offset:34816
	ds_read_b128 v[188:191], v147 offset:35840
	ds_read_b128 v[192:195], v147 offset:36864
	ds_read_b128 v[196:199], v147 offset:37888
	ds_read_b128 v[200:203], v147 offset:38912
	ds_read_b128 v[204:207], v147 offset:39936
	global_load_lds_dwordx4 v[216:217], off
	v_lshl_add_u64 v[216:217], s[38:39], 0, v[132:133]
	s_mov_b32 m0, s47
	s_nop 0
	global_load_lds_dwordx4 v[216:217], off
	s_waitcnt vmcnt(8)
	s_waitcnt lgkmcnt(0)
	s_barrier
	s_waitcnt lgkmcnt(0)
	v_mfma_f32_16x16x32_bf16 v[122:125], v[140:143], v[176:179], v[122:125]
	v_mfma_f32_16x16x32_bf16 v[122:125], v[148:151], v[180:183], v[122:125]
	v_mfma_f32_16x16x32_bf16 v[114:117], v[152:155], v[176:179], v[114:117]
	v_mfma_f32_16x16x32_bf16 v[114:117], v[156:159], v[180:183], v[114:117]
	v_mfma_f32_16x16x32_bf16 v[106:109], v[140:143], v[184:187], v[106:109]
	v_mfma_f32_16x16x32_bf16 v[106:109], v[148:151], v[188:191], v[106:109]
	v_mfma_f32_16x16x32_bf16 v[98:101], v[152:155], v[184:187], v[98:101]
	v_mfma_f32_16x16x32_bf16 v[98:101], v[156:159], v[188:191], v[98:101]
	v_mfma_f32_16x16x32_bf16 v[90:93], v[140:143], v[192:195], v[90:93]
	v_mfma_f32_16x16x32_bf16 v[90:93], v[148:151], v[196:199], v[90:93]
	v_mfma_f32_16x16x32_bf16 v[82:85], v[152:155], v[192:195], v[82:85]
	v_mfma_f32_16x16x32_bf16 v[82:85], v[156:159], v[196:199], v[82:85]
	v_mfma_f32_16x16x32_bf16 v[74:77], v[140:143], v[200:203], v[74:77]
	v_mfma_f32_16x16x32_bf16 v[74:77], v[148:151], v[204:207], v[74:77]
	v_mfma_f32_16x16x32_bf16 v[66:69], v[152:155], v[200:203], v[66:69]
	v_mfma_f32_16x16x32_bf16 v[66:69], v[156:159], v[204:207], v[66:69]
	v_mfma_f32_16x16x32_bf16 v[126:129], v[160:163], v[176:179], v[126:129]
	v_mfma_f32_16x16x32_bf16 v[126:129], v[164:167], v[180:183], v[126:129]
	v_mfma_f32_16x16x32_bf16 v[118:121], v[168:171], v[176:179], v[118:121]
	v_mfma_f32_16x16x32_bf16 v[118:121], v[172:175], v[180:183], v[118:121]
	v_mfma_f32_16x16x32_bf16 v[110:113], v[160:163], v[184:187], v[110:113]
	v_mfma_f32_16x16x32_bf16 v[110:113], v[164:167], v[188:191], v[110:113]
	v_mfma_f32_16x16x32_bf16 v[102:105], v[168:171], v[184:187], v[102:105]
	v_mfma_f32_16x16x32_bf16 v[102:105], v[172:175], v[188:191], v[102:105]
	v_mfma_f32_16x16x32_bf16 v[94:97], v[160:163], v[192:195], v[94:97]
	v_mfma_f32_16x16x32_bf16 v[94:97], v[164:167], v[196:199], v[94:97]
	v_mfma_f32_16x16x32_bf16 v[86:89], v[168:171], v[192:195], v[86:89]
	v_mfma_f32_16x16x32_bf16 v[86:89], v[172:175], v[196:199], v[86:89]
	v_mfma_f32_16x16x32_bf16 v[78:81], v[160:163], v[200:203], v[78:81]
	v_mfma_f32_16x16x32_bf16 v[78:81], v[164:167], v[204:207], v[78:81]
	v_mfma_f32_16x16x32_bf16 v[70:73], v[168:171], v[200:203], v[70:73]
	v_mfma_f32_16x16x32_bf16 v[70:73], v[172:175], v[204:207], v[70:73]
	s_barrier
	s_add_i32 s38, s57, s43
	v_lshl_add_u64 v[208:209], v[208:209], 0, s[98:99]
	s_mov_b32 m0, s38
	ds_read_b128 v[176:179], v147 offset:49152
	ds_read_b128 v[180:183], v147 offset:50176
	ds_read_b128 v[184:187], v147 offset:51200
	ds_read_b128 v[188:191], v147 offset:52224
	ds_read_b128 v[192:195], v147 offset:53248
	ds_read_b128 v[196:199], v147 offset:54272
	ds_read_b128 v[200:203], v147 offset:55296
	ds_read_b128 v[204:207], v147 offset:56320
	global_load_lds_dwordx4 v[208:209], off
	s_add_i32 m0, s38, 0x2000
	s_add_u32 s30, s30, 0x40080
	v_lshl_add_u64 v[208:209], v[210:211], 0, s[98:99]
	s_addc_u32 s31, s31, 0
	s_add_i32 s38, s58, s43
	global_load_lds_dwordx4 v[208:209], off
	v_lshl_add_u64 v[208:209], s[30:31], 0, v[0:1]
	s_mov_b32 m0, s38
	s_nop 0
	global_load_lds_dwordx4 v[208:209], off
	v_lshl_add_u64 v[208:209], s[30:31], 0, v[134:135]
	s_add_i32 m0, s38, 0x2000
	s_nop 0
	global_load_lds_dwordx4 v[208:209], off
	v_lshl_add_u64 v[208:209], v[212:213], 0, s[98:99]
	s_mov_b32 m0, s49
	s_nop 0
	global_load_lds_dwordx4 v[208:209], off
	v_lshl_add_u64 v[208:209], v[214:215], 0, s[98:99]
	s_mov_b32 m0, s51
	s_nop 0
	global_load_lds_dwordx4 v[208:209], off
	s_waitcnt vmcnt(8)
	s_waitcnt lgkmcnt(0)
	s_barrier
	s_waitcnt lgkmcnt(0)
	v_mfma_f32_16x16x32_bf16 v[58:61], v[140:143], v[176:179], v[58:61]
	v_mfma_f32_16x16x32_bf16 v[58:61], v[148:151], v[180:183], v[58:61]
	v_mfma_f32_16x16x32_bf16 v[50:53], v[152:155], v[176:179], v[50:53]
	v_mfma_f32_16x16x32_bf16 v[50:53], v[156:159], v[180:183], v[50:53]
	v_mfma_f32_16x16x32_bf16 v[42:45], v[140:143], v[184:187], v[42:45]
	v_mfma_f32_16x16x32_bf16 v[42:45], v[148:151], v[188:191], v[42:45]
	v_mfma_f32_16x16x32_bf16 v[34:37], v[152:155], v[184:187], v[34:37]
	v_mfma_f32_16x16x32_bf16 v[34:37], v[156:159], v[188:191], v[34:37]
	v_mfma_f32_16x16x32_bf16 v[26:29], v[140:143], v[192:195], v[26:29]
	v_mfma_f32_16x16x32_bf16 v[26:29], v[148:151], v[196:199], v[26:29]
	v_mfma_f32_16x16x32_bf16 v[18:21], v[152:155], v[192:195], v[18:21]
	v_mfma_f32_16x16x32_bf16 v[18:21], v[156:159], v[196:199], v[18:21]
	v_mfma_f32_16x16x32_bf16 v[10:13], v[140:143], v[200:203], v[10:13]
	v_mfma_f32_16x16x32_bf16 v[10:13], v[148:151], v[204:207], v[10:13]
	v_mfma_f32_16x16x32_bf16 v[6:9], v[152:155], v[200:203], v[6:9]
	v_mfma_f32_16x16x32_bf16 v[6:9], v[156:159], v[204:207], v[6:9]
	v_mfma_f32_16x16x32_bf16 v[62:65], v[160:163], v[176:179], v[62:65]
	v_mfma_f32_16x16x32_bf16 v[62:65], v[164:167], v[180:183], v[62:65]
	v_mfma_f32_16x16x32_bf16 v[54:57], v[168:171], v[176:179], v[54:57]
	v_mfma_f32_16x16x32_bf16 v[54:57], v[172:175], v[180:183], v[54:57]
	v_mfma_f32_16x16x32_bf16 v[46:49], v[160:163], v[184:187], v[46:49]
	v_mfma_f32_16x16x32_bf16 v[46:49], v[164:167], v[188:191], v[46:49]
	v_mfma_f32_16x16x32_bf16 v[38:41], v[168:171], v[184:187], v[38:41]
	v_mfma_f32_16x16x32_bf16 v[38:41], v[172:175], v[188:191], v[38:41]
	v_mfma_f32_16x16x32_bf16 v[30:33], v[160:163], v[192:195], v[30:33]
	v_mfma_f32_16x16x32_bf16 v[30:33], v[164:167], v[196:199], v[30:33]
	v_mfma_f32_16x16x32_bf16 v[22:25], v[168:171], v[192:195], v[22:25]
	v_mfma_f32_16x16x32_bf16 v[22:25], v[172:175], v[196:199], v[22:25]
	v_mfma_f32_16x16x32_bf16 v[14:17], v[160:163], v[200:203], v[14:17]
	v_mfma_f32_16x16x32_bf16 v[14:17], v[164:167], v[204:207], v[14:17]
	v_mfma_f32_16x16x32_bf16 v[2:5], v[168:171], v[200:203], v[2:5]
	v_mfma_f32_16x16x32_bf16 v[2:5], v[172:175], v[204:207], v[2:5]
	s_barrier
	s_add_i32 s56, s56, 2
	s_add_u32 s28, s28, 0x100
	s_addc_u32 s29, s29, 0
	s_add_u32 s54, s54, 0x100
	s_addc_u32 s55, s55, 0
	s_cmp_gt_u32 s56, 13
	s_cbranch_scc0 .LBB0_374
